# KI key relayout for coalesced topk loads, radix bit loop with 16 independent ballots, k11 GEMM loop fragment double buffering
# speedup vs baseline: 1.0229x; 1.0229x over previous
.Lxk_166:
	ds_read_b128 v[220:223], v136
	ds_read_b128 v[224:227], v136 offset:2048
	ds_read_b128 v[228:231], v136 offset:4096
	ds_read_b128 v[232:235], v136 offset:6144
	ds_read_b128 v[236:239], v137 offset:16384
	ds_read_b128 v[240:243], v137 offset:18432
	ds_read_b128 v[244:247], v137 offset:20480
	ds_read_b128 v[248:251], v137 offset:22528
	s_waitcnt lgkmcnt(8)
	v_mfma_f32_16x16x32_bf16 v[124:127], v[154:157], v[138:141], v[124:127]
	s_add_i32 s9, s9, 2
	v_mfma_f32_16x16x32_bf16 v[120:123], v[158:161], v[138:141], v[120:123]
	s_min_u32 s11, s9, 60
	v_mfma_f32_16x16x32_bf16 v[116:119], v[162:165], v[138:141], v[116:119]
	s_lshl_b32 s56, s11, 7
	v_mfma_f32_16x16x32_bf16 v[112:115], v[166:169], v[138:141], v[112:115]
	s_min_u32 s11, s9, 59
	v_mfma_f32_16x16x32_bf16 v[108:111], v[154:157], v[142:145], v[108:111]
	s_waitcnt vmcnt(15)
	v_mfma_f32_16x16x32_bf16 v[104:107], v[158:161], v[142:145], v[104:107]
	ds_write_b128 v133, v[0:3] offset:32768
	v_mfma_f32_16x16x32_bf16 v[100:103], v[162:165], v[142:145], v[100:103]
	s_waitcnt vmcnt(11)
	v_mfma_f32_16x16x32_bf16 v[96:99], v[166:169], v[142:145], v[96:99]
	ds_write_b128 v133, v[8:11] offset:49152
	v_mfma_f32_16x16x32_bf16 v[92:95], v[154:157], v[146:149], v[92:95]
	ds_write_b128 v133, v[4:7] offset:36864
	v_mfma_f32_16x16x32_bf16 v[88:91], v[158:161], v[146:149], v[88:91]
	s_waitcnt vmcnt(10)
	v_mfma_f32_16x16x32_bf16 v[84:87], v[162:165], v[146:149], v[84:87]
	ds_write_b128 v133, v[12:15] offset:53248
	v_mfma_f32_16x16x32_bf16 v[80:83], v[166:169], v[146:149], v[80:83]
	ds_write_b128 v133, v[16:19] offset:40960
	v_mfma_f32_16x16x32_bf16 v[76:79], v[154:157], v[150:153], v[76:79]
	s_waitcnt vmcnt(9)
	v_mfma_f32_16x16x32_bf16 v[72:75], v[158:161], v[150:153], v[72:75]
	ds_write_b128 v133, v[20:23] offset:57344
	v_mfma_f32_16x16x32_bf16 v[68:71], v[162:165], v[150:153], v[68:71]
	ds_write_b128 v133, v[24:27] offset:45056
	v_mfma_f32_16x16x32_bf16 v[64:67], v[166:169], v[150:153], v[64:67]
	s_waitcnt vmcnt(8)
	ds_write_b128 v133, v[28:31] offset:61440
	s_waitcnt lgkmcnt(0)
	s_barrier
	ds_read_b128 v[138:141], v134 offset:32768
	ds_read_b128 v[142:145], v134 offset:34816
	ds_read_b128 v[146:149], v134 offset:36864
	ds_read_b128 v[150:153], v134 offset:38912
	ds_read_b128 v[154:157], v135 offset:49152
	ds_read_b128 v[158:161], v135 offset:51200
	ds_read_b128 v[162:165], v135 offset:53248
	ds_read_b128 v[166:169], v135 offset:55296
	v_mfma_f32_16x16x32_bf16 v[124:127], v[236:239], v[220:223], v[124:127]
	v_lshl_add_u64 v[24:25], v[128:129], 0, s[56:57]
	v_mfma_f32_16x16x32_bf16 v[120:123], v[240:243], v[220:223], v[120:123]
	v_add_co_u32_e32 v4, vcc, s33, v24
	v_lshl_add_u64 v[28:29], v[130:131], 0, s[56:57]
	v_mfma_f32_16x16x32_bf16 v[116:119], v[244:247], v[220:223], v[116:119]
	s_nop 0
	v_mfma_f32_16x16x32_bf16 v[112:115], v[248:251], v[220:223], v[112:115]
	v_addc_co_u32_e32 v5, vcc, 0, v25, vcc
	v_add_co_u32_e32 v12, vcc, s33, v28
	v_mfma_f32_16x16x32_bf16 v[108:111], v[236:239], v[224:227], v[108:111]
	global_load_dwordx4 v[0:3], v[24:25], off offset:384
	v_mfma_f32_16x16x32_bf16 v[104:107], v[240:243], v[224:227], v[104:107]
	global_load_dwordx4 v[8:11], v[28:29], off offset:384
	v_addc_co_u32_e32 v13, vcc, 0, v29, vcc
	v_mfma_f32_16x16x32_bf16 v[100:103], v[244:247], v[224:227], v[100:103]
	v_add_co_u32_e32 v16, vcc, s12, v24
	v_mfma_f32_16x16x32_bf16 v[96:99], v[248:251], v[224:227], v[96:99]
	s_nop 0
	v_addc_co_u32_e32 v17, vcc, 0, v25, vcc
	v_add_co_u32_e32 v20, vcc, s12, v28
	v_mfma_f32_16x16x32_bf16 v[92:95], v[236:239], v[228:231], v[92:95]
	s_nop 0
	v_addc_co_u32_e32 v21, vcc, 0, v29, vcc
	v_add_co_u32_e32 v24, vcc, s13, v24
	v_mfma_f32_16x16x32_bf16 v[88:91], v[240:243], v[228:231], v[88:91]
	s_nop 0
	v_addc_co_u32_e32 v25, vcc, 0, v25, vcc
	v_mfma_f32_16x16x32_bf16 v[84:87], v[244:247], v[228:231], v[84:87]
	v_add_co_u32_e32 v28, vcc, s13, v28
	s_nop 1
	v_addc_co_u32_e32 v29, vcc, 0, v29, vcc
	v_mfma_f32_16x16x32_bf16 v[80:83], v[248:251], v[228:231], v[80:83]
	global_load_dwordx4 v[4:7], v[4:5], off offset:384
	v_mfma_f32_16x16x32_bf16 v[76:79], v[236:239], v[232:235], v[76:79]
	global_load_dwordx4 v[12:15], v[12:13], off offset:384
	s_lshl_b32 s56, s11, 7
	v_mfma_f32_16x16x32_bf16 v[72:75], v[240:243], v[232:235], v[72:75]
	global_load_dwordx4 v[16:19], v[16:17], off offset:384
	v_mfma_f32_16x16x32_bf16 v[68:71], v[244:247], v[232:235], v[68:71]
	global_load_dwordx4 v[20:23], v[20:21], off offset:384
	s_cmp_lt_u32 s9, 62
	v_mfma_f32_16x16x32_bf16 v[64:67], v[248:251], v[232:235], v[64:67]
	global_load_dwordx4 v[24:27], v[24:25], off offset:384
	global_load_dwordx4 v[28:31], v[28:29], off offset:384
	ds_read_b128 v[220:223], v136 offset:32768
	ds_read_b128 v[224:227], v136 offset:34816
	ds_read_b128 v[228:231], v136 offset:36864
	ds_read_b128 v[232:235], v136 offset:38912
	ds_read_b128 v[236:239], v137 offset:49152
	ds_read_b128 v[240:243], v137 offset:51200
	ds_read_b128 v[244:247], v137 offset:53248
	ds_read_b128 v[248:251], v137 offset:55296
	s_waitcnt lgkmcnt(8)
	v_mfma_f32_16x16x32_bf16 v[124:127], v[154:157], v[138:141], v[124:127]
	s_waitcnt vmcnt(15)
	v_mfma_f32_16x16x32_bf16 v[120:123], v[158:161], v[138:141], v[120:123]
	ds_write_b128 v133, v[32:35]
	v_mfma_f32_16x16x32_bf16 v[116:119], v[162:165], v[138:141], v[116:119]
	s_waitcnt vmcnt(14)
	v_mfma_f32_16x16x32_bf16 v[112:115], v[166:169], v[138:141], v[112:115]
	ds_write_b128 v133, v[36:39] offset:16384
	v_mfma_f32_16x16x32_bf16 v[108:111], v[154:157], v[142:145], v[108:111]
	s_waitcnt vmcnt(13)
	v_mfma_f32_16x16x32_bf16 v[104:107], v[158:161], v[142:145], v[104:107]
	ds_write_b128 v133, v[40:43] offset:4096
	v_mfma_f32_16x16x32_bf16 v[100:103], v[162:165], v[142:145], v[100:103]
	s_waitcnt vmcnt(12)
	v_mfma_f32_16x16x32_bf16 v[96:99], v[166:169], v[142:145], v[96:99]
	ds_write_b128 v133, v[44:47] offset:20480
	v_mfma_f32_16x16x32_bf16 v[92:95], v[154:157], v[146:149], v[92:95]
	s_waitcnt vmcnt(11)
	v_mfma_f32_16x16x32_bf16 v[88:91], v[158:161], v[146:149], v[88:91]
	ds_write_b128 v133, v[48:51] offset:8192
	v_mfma_f32_16x16x32_bf16 v[84:87], v[162:165], v[146:149], v[84:87]
	s_waitcnt vmcnt(10)
	v_mfma_f32_16x16x32_bf16 v[80:83], v[166:169], v[146:149], v[80:83]
	ds_write_b128 v133, v[52:55] offset:24576
	v_mfma_f32_16x16x32_bf16 v[76:79], v[154:157], v[150:153], v[76:79]
	s_waitcnt vmcnt(9)
	v_mfma_f32_16x16x32_bf16 v[72:75], v[158:161], v[150:153], v[72:75]
	ds_write_b128 v133, v[56:59] offset:12288
	v_mfma_f32_16x16x32_bf16 v[68:71], v[162:165], v[150:153], v[68:71]
	s_waitcnt vmcnt(8)
	v_mfma_f32_16x16x32_bf16 v[64:67], v[166:169], v[150:153], v[64:67]
	ds_write_b128 v133, v[60:63] offset:28672
	s_waitcnt lgkmcnt(0)
	s_barrier
	ds_read_b128 v[138:141], v134
	ds_read_b128 v[142:145], v134 offset:2048
	ds_read_b128 v[146:149], v134 offset:4096
	ds_read_b128 v[150:153], v134 offset:6144
	ds_read_b128 v[154:157], v135 offset:16384
	ds_read_b128 v[158:161], v135 offset:18432
	ds_read_b128 v[162:165], v135 offset:20480
	ds_read_b128 v[166:169], v135 offset:22528
	v_mfma_f32_16x16x32_bf16 v[124:127], v[236:239], v[220:223], v[124:127]
	v_lshl_add_u64 v[56:57], v[128:129], 0, s[56:57]
	v_mfma_f32_16x16x32_bf16 v[120:123], v[240:243], v[220:223], v[120:123]
	v_add_co_u32_e32 v40, vcc, s33, v56
	v_lshl_add_u64 v[60:61], v[130:131], 0, s[56:57]
	v_mfma_f32_16x16x32_bf16 v[116:119], v[244:247], v[220:223], v[116:119]
	s_nop 0
	v_addc_co_u32_e32 v41, vcc, 0, v57, vcc
	v_mfma_f32_16x16x32_bf16 v[112:115], v[248:251], v[220:223], v[112:115]
	v_add_co_u32_e32 v44, vcc, s33, v60
	v_mfma_f32_16x16x32_bf16 v[108:111], v[236:239], v[224:227], v[108:111]
	global_load_dwordx4 v[32:35], v[56:57], off offset:512
	global_load_dwordx4 v[36:39], v[60:61], off offset:512
	v_mfma_f32_16x16x32_bf16 v[104:107], v[240:243], v[224:227], v[104:107]
	v_addc_co_u32_e32 v45, vcc, 0, v61, vcc
	v_add_co_u32_e32 v48, vcc, s12, v56
	v_mfma_f32_16x16x32_bf16 v[100:103], v[244:247], v[224:227], v[100:103]
	global_load_dwordx4 v[40:43], v[40:41], off offset:512
	v_mfma_f32_16x16x32_bf16 v[96:99], v[248:251], v[224:227], v[96:99]
	s_nop 0
	v_addc_co_u32_e32 v49, vcc, 0, v57, vcc
	v_mfma_f32_16x16x32_bf16 v[92:95], v[236:239], v[228:231], v[92:95]
	v_add_co_u32_e32 v52, vcc, s12, v60
	global_load_dwordx4 v[44:47], v[44:45], off offset:512
	v_mfma_f32_16x16x32_bf16 v[88:91], v[240:243], v[228:231], v[88:91]
	s_nop 0
	v_mfma_f32_16x16x32_bf16 v[84:87], v[244:247], v[228:231], v[84:87]
	v_addc_co_u32_e32 v53, vcc, 0, v61, vcc
	v_add_co_u32_e32 v56, vcc, s13, v56
	v_mfma_f32_16x16x32_bf16 v[80:83], v[248:251], v[228:231], v[80:83]
	global_load_dwordx4 v[48:51], v[48:49], off offset:512
	s_nop 0
	v_mfma_f32_16x16x32_bf16 v[76:79], v[236:239], v[232:235], v[76:79]
	v_addc_co_u32_e32 v57, vcc, 0, v57, vcc
	v_mfma_f32_16x16x32_bf16 v[72:75], v[240:243], v[232:235], v[72:75]
	v_add_co_u32_e32 v60, vcc, s13, v60
	global_load_dwordx4 v[52:55], v[52:53], off offset:512
	v_mfma_f32_16x16x32_bf16 v[68:71], v[244:247], v[232:235], v[68:71]
	s_nop 0
	v_addc_co_u32_e32 v61, vcc, 0, v61, vcc
	v_mfma_f32_16x16x32_bf16 v[64:67], v[248:251], v[232:235], v[64:67]
	global_load_dwordx4 v[56:59], v[56:57], off offset:512
	global_load_dwordx4 v[60:63], v[60:61], off offset:512
	s_cbranch_scc1 .Lxk_166
	s_waitcnt vmcnt(0) lgkmcnt(0)
	s_waitcnt vmcnt(14)
	v_mov_b32_e32 v11, v192
	s_lshl_b32 s9, s10, 7
	v_lshlrev_b32_e32 v2, 8, v11
	v_and_b32_e32 v0, 15, v11
	v_bfe_u32 v1, v11, 4, 2
	v_and_b32_e32 v10, 0xffffc000, v2
	v_lshl_or_b32 v2, v0, 8, v10
	v_bitop3_b32 v3, v1, v11, 15 bitop3:0x78
	s_waitcnt vmcnt(13)
	v_bitop3_b32 v4, v1, v0, 4 bitop3:0x36
	v_bitop3_b32 v5, v1, v0, 8 bitop3:0x36
	v_bitop3_b32 v0, v1, v0, 12 bitop3:0x36
	v_lshl_or_b32 v3, v3, 4, v2
	v_lshl_or_b32 v4, v4, 4, v2
	v_lshl_or_b32 v5, v5, 4, v2
	v_lshl_or_b32 v0, v0, 4, v2
	s_waitcnt vmcnt(12)
	v_and_b32_e32 v12, 7, v11
	ds_write_b128 v3, v[124:127]
	ds_write_b128 v4, v[120:123]
	ds_write_b128 v5, v[116:119]
	ds_write_b128 v0, v[112:115]
	ds_write_b128 v3, v[108:111] offset:4096
	ds_write_b128 v4, v[104:107] offset:4096
	ds_write_b128 v5, v[100:103] offset:4096
	ds_write_b128 v0, v[96:99] offset:4096
	ds_write_b128 v3, v[92:95] offset:8192
	ds_write_b128 v4, v[88:91] offset:8192
	ds_write_b128 v5, v[84:87] offset:8192
	ds_write_b128 v0, v[80:83] offset:8192
	ds_write_b128 v3, v[76:79] offset:12288
	ds_write_b128 v4, v[72:75] offset:12288
	ds_write_b128 v5, v[68:71] offset:12288
	ds_write_b128 v0, v[64:67] offset:12288
	v_and_b32_e32 v0, 64, v11
	v_lshlrev_b32_e32 v1, 3, v12
	v_or3_b32 v8, v0, s9, v1
	s_andn2_b64 vcc, exec, s[6:7]
	v_ashrrev_i32_e32 v9, 31, v8
	s_movk_i32 s10, 0x401f
	s_cbranch_vccz .LBB0_159
	v_mov_b32_e32 v0, 0
	v_mov_b32_e32 v1, 0
	v_mov_b32_e32 v2, 0
	v_mov_b32_e32 v3, 0
	v_mov_b32_e32 v4, 0
	v_mov_b32_e32 v5, 0
	v_mov_b32_e32 v6, 0
	v_mov_b32_e32 v7, 0
	s_branch .LBB0_160

.LBB0_295:
	s_or_b64 exec, exec, s[0:1]
	v_mov_b32_e32 v141, v192
	s_load_dword s6, s[42:43], 0x0
	s_load_dword s4, s[42:43], 0x10
	s_waitcnt lgkmcnt(0)
	s_add_u32 s0, s2, 0xdb44000
	s_addc_u32 s1, s3, 0
	v_writelane_b32 v252, s0, 24
	s_mov_b32 s5, 0
	s_waitcnt vmcnt(0)
	v_lshrrev_b32_e32 v0, 2, v141
	v_writelane_b32 v252, s1, 25
	s_add_u32 s0, s2, 0xdbc5000
	s_addc_u32 s1, s3, 0
	s_lshr_b32 s4, s4, 16
	s_cmp_lg_u32 s4, 0
	v_writelane_b32 v252, s5, 26
	s_cselect_b64 s[4:5], -1, 0
	s_cmp_lg_u64 s[4:5], 0
	s_addc_u32 s4, s6, 0
	v_and_b32_e32 v1, 1, v141
	v_writelane_b32 v252, s4, 27
	s_movk_i32 s4, 0x2000
	v_cmp_gt_i32_e64 s[4:5], s4, v141
	v_and_or_b32 v0, v0, 6, v1
	v_bfe_u32 v2, v141, 5, 1
	v_writelane_b32 v252, s4, 28
	v_lshlrev_b32_e32 v176, 7, v0
	v_lshl_add_u64 v[0:1], s[2:3], 0, v[176:177]
	v_writelane_b32 v252, s5, 29
	s_movk_i32 s4, 0x840
	v_cmp_gt_i32_e64 s[4:5], s4, v141
	v_lshlrev_b32_e32 v176, 4, v2
	v_lshl_add_u64 v[0:1], v[0:1], 0, v[176:177]
	v_writelane_b32 v252, s4, 30
	v_and_b32_e32 v156, 63, v141
	v_and_b32_e32 v157, 31, v141
	v_writelane_b32 v252, s5, 31
	v_cmp_gt_i32_e64 s[4:5], 32, v141
	v_ashrrev_i32_e32 v132, 6, v141
	v_lshlrev_b32_e32 v138, 4, v132
	v_writelane_b32 v252, s4, 32
	v_lshlrev_b32_e32 v160, 3, v2
	v_lshlrev_b32_e32 v161, 1, v2
	v_writelane_b32 v252, s5, 33
	s_mov_b64 s[4:5], 0x5840000
	v_lshl_add_u64 v[134:135], v[0:1], 0, s[4:5]
	v_lshlrev_b32_e32 v176, 4, v156
	v_lshl_add_u64 v[0:1], s[2:3], 0, v[176:177]
	s_mov_b64 s[4:5], 0xd940000
	v_lshl_add_u64 v[136:137], v[0:1], 0, s[4:5]
	v_cmp_gt_u32_e64 s[4:5], 2, v156
	v_lshlrev_b32_e32 v0, 4, v156
	v_lshlrev_b32_e32 v140, 3, v132
	v_writelane_b32 v252, s4, 34
	v_mul_u32_u24_e32 v166, 5, v156
	v_ashrrev_i32_e32 v139, 31, v138
	v_writelane_b32 v252, s5, 35
	v_cmp_gt_u32_e64 s[4:5], 4, v156
	v_ashrrev_i32_e32 v133, 31, v132
	v_sub_u32_e32 v164, 0, v0
	v_writelane_b32 v252, s4, 36
	v_or_b32_e32 v167, 1, v161
	v_lshlrev_b64 v[142:143], 12, v[138:139]
	v_writelane_b32 v252, s5, 37
	v_cmp_gt_u32_e64 s[4:5], 8, v156
	v_lshlrev_b64 v[144:145], 12, v[132:133]
	v_mul_i32_i24_e32 v133, 0xffffe008, v2
	v_writelane_b32 v252, s4, 38
	v_lshlrev_b32_e32 v173, 11, v2
	v_mul_u32_u24_e32 v0, 0x840, v2
	v_writelane_b32 v252, s5, 39
	v_cmp_eq_u32_e64 s[4:5], 0, v157
	v_mul_u32_u24_e32 v1, 0x420, v167
	v_lshlrev_b32_e32 v162, 1, v132
	v_writelane_b32 v252, s4, 40
	v_or_b32_e32 v179, 1, v162
	v_lshlrev_b32_e32 v159, 2, v141
	v_writelane_b32 v252, s5, 41
	v_cmp_gt_u32_e64 s[4:5], 2, v157
	v_lshlrev_b32_e32 v163, 6, v156
	v_or_b32_e32 v168, 4, v161
	v_writelane_b32 v252, s4, 42
	v_or_b32_e32 v169, 5, v161
	v_lshlrev_b32_e32 v180, 12, v179
	v_writelane_b32 v252, s5, 43
	v_cmp_gt_u32_e64 s[4:5], 4, v157
	v_bfe_u32 v158, v141, 1, 2
	v_cmp_eq_u32_e64 s[44:45], 0, v156
	v_writelane_b32 v252, s4, 44
	v_cmp_gt_u32_e64 s[52:53], 16, v156
	v_cmp_gt_u32_e64 s[54:55], 32, v156
	v_writelane_b32 v252, s5, 45
	v_cmp_gt_u32_e64 s[4:5], 8, v157
	v_lshlrev_b32_e64 v165, v141, 1
	v_cmp_ne_u32_e64 s[68:69], 0, v156
	v_writelane_b32 v252, s4, 46
	v_lshlrev_b32_e32 v170, 12, v167
	v_lshlrev_b32_e32 v171, 12, v168
	v_writelane_b32 v252, s5, 47
	v_cmp_gt_u32_e64 s[4:5], 16, v157
	v_lshlrev_b32_e32 v172, 12, v169
	v_lshlrev_b32_e32 v174, 10, v167
	v_writelane_b32 v252, s4, 48
	v_lshlrev_b32_e32 v175, 10, v168
	v_lshlrev_b32_e32 v178, 10, v169
	v_writelane_b32 v252, s5, 49
	v_cmp_gt_i32_e64 s[4:5], 8, v141
	v_sub_u32_e32 v181, v180, v163
	v_or_b32_e32 v182, 64, v156
	v_writelane_b32 v252, s4, 50
	v_or_b32_e32 v183, 0x80, v156
	v_or_b32_e32 v184, 0xc0, v156
	v_writelane_b32 v252, s5, 51
	s_movk_i32 s4, 0x1ff8
	v_mad_u32_u24 v139, v2, s4, v160
	v_mad_u64_u32 v[146:147], s[4:5], v132, s4, v[140:141]
	v_lshlrev_b32_e32 v2, 5, v166
	v_add_u32_e32 v225, 32, v2
	v_add_u32_e32 v226, 64, v2
	v_add_u32_e32 v227, 0x60, v2
	v_add_u32_e32 v228, 0x80, v2
	v_lshlrev_b32_e32 v2, 2, v132
	s_mov_b32 s4, 0xc000
	v_add3_u32 v233, v1, v2, s4
	v_add3_u32 v234, v0, v2, s4
	v_or_b32_e32 v0, v144, v176
	v_mov_b32_e32 v1, v145
	v_lshl_add_u64 v[0:1], s[2:3], 0, v[0:1]
	s_mov_b64 s[2:3], 0xd940000
	v_lshl_add_u64 v[148:149], v[0:1], 0, s[2:3]
	v_lshlrev_b32_e32 v0, 12, v132
	v_add_u32_e32 v235, 0x8000, v0
	v_lshl_or_b32 v0, v156, 1, v0
	v_sub_u32_e32 v147, v146, v163
	v_or_b32_e32 v185, 0x100, v156
	v_or_b32_e32 v186, 0x140, v156
	v_or_b32_e32 v187, 0x180, v156
	v_or_b32_e32 v188, 0x1c0, v156
	v_or_b32_e32 v189, 0x200, v156
	v_or_b32_e32 v190, 0x240, v156
	v_or_b32_e32 v191, 0x280, v156
	v_or_b32_e32 v219, 0x2c0, v156
	v_or_b32_e32 v220, 0x300, v156
	v_or_b32_e32 v221, 0x340, v156
	v_or_b32_e32 v222, 0x380, v156
	v_or_b32_e32 v223, 0x3c0, v156
	v_cmp_gt_u32_e64 s[70:71], 52, v156
	v_cmp_gt_u32_e64 s[72:73], 51, v156
	v_mul_u32_u24_e32 v224, 0xa0, v156
	v_add_u32_e32 v229, 0xffffff00, v141
	v_add_u32_e32 v230, 0xc000, v159
	v_lshl_or_b32 v231, v132, 9, v157
	v_lshl_or_b32 v232, v132, 5, v157
	v_add_u32_e32 v236, 0x8000, v0
	v_add_u32_e32 v237, 0x2008, v162
	s_mov_b32 s2, 0
	v_writelane_b32 v252, s2, 52
	s_branch .LBB0_298

.LBB0_309:
	s_or_b64 exec, exec, s[2:3]
	s_mov_b64 s[2:3], exec
	v_readlane_b32 s4, v252, 32
	v_readlane_b32 s5, v252, 33
	s_and_b64 s[4:5], s[2:3], s[4:5]
	s_mov_b64 exec, s[4:5]
	ds_write_b32 v159, v177 offset:57600
	s_or_b64 exec, exec, s[2:3]
	s_lshl_b32 s2, s6, 2
	s_and_b32 s10, s2, -8
	s_sub_i32 s7, 0x2008, s10
	s_bitcmp1_b32 s6, 0
	s_cselect_b32 s5, 0x2010, 0
	s_add_i32 s4, s7, s5
	v_or_b32_e32 v176, s4, v158
	v_lshlrev_b64 v[0:1], 10, v[176:177]
	v_lshl_add_u64 v[0:1], v[134:135], 0, v[0:1]
	global_load_dwordx4 v[32:35], v[0:1], off
	global_load_dwordx4 v[36:39], v[0:1], off offset:32
	global_load_dwordx4 v[40:43], v[0:1], off offset:64
	global_load_dwordx4 v[44:47], v[0:1], off offset:96
	v_or_b32_e32 v0, s4, v161
	v_mov_b32_e32 v1, v177
	v_readlane_b32 s2, v252, 24
	v_lshlrev_b64 v[0:1], 5, v[0:1]
	v_readlane_b32 s3, v252, 25
	v_or_b32_e32 v176, 4, v176
	v_writelane_b32 v252, s4, 54
	v_lshl_add_u64 v[0:1], s[2:3], 0, v[0:1]
	global_load_dwordx4 v[48:51], v[0:1], off
	global_load_dwordx4 v[52:55], v[0:1], off offset:16
	global_load_dwordx4 v[56:59], v[0:1], off offset:32
	global_load_dwordx4 v[60:63], v[0:1], off offset:48
	v_lshlrev_b64 v[0:1], 10, v[176:177]
	v_lshl_add_u64 v[0:1], v[134:135], 0, v[0:1]
	v_or_b32_e32 v176, s4, v168
	global_load_dwordx4 v[64:67], v[0:1], off
	global_load_dwordx4 v[68:71], v[0:1], off offset:32
	global_load_dwordx4 v[72:75], v[0:1], off offset:64
	global_load_dwordx4 v[76:79], v[0:1], off offset:96
	v_lshlrev_b64 v[0:1], 5, v[176:177]
	v_lshl_add_u64 v[0:1], s[2:3], 0, v[0:1]
	global_load_dwordx4 v[80:83], v[0:1], off
	global_load_dwordx4 v[84:87], v[0:1], off offset:16
	global_load_dwordx4 v[88:91], v[0:1], off offset:32
	global_load_dwordx4 v[92:95], v[0:1], off offset:48
	s_lshr_b32 s2, s5, 9
	s_add_i32 s2, s2, s5
	v_mov_b32_e32 v0, s2
	s_lshr_b32 s18, s7, 5
	s_add_i32 s2, s10, 0xffffdfef
	v_lshlrev_b32_e32 v176, 7, v0
	s_cmpk_gt_i32 s2, 0xfbfe
	v_or_b32_e32 v238, s7, v161
	v_or_b32_e32 v239, s7, v167
	v_or_b32_e32 v240, s7, v168
	v_writelane_b32 v252, s7, 55
	v_or_b32_e32 v241, s7, v169
	v_lshl_add_u64 v[154:155], v[136:137], 0, v[176:177]
	v_writelane_b32 v252, s5, 56
	s_waitcnt lgkmcnt(0)
	s_barrier
	s_cbranch_scc1 .LBB0_343
	v_cmp_ge_i32_e32 vcc, s18, v138
	s_and_saveexec_b64 s[2:3], vcc
	s_cbranch_execz .LBB0_331
	v_lshl_add_u64 v[0:1], v[154:155], 0, v[142:143]
	global_load_dwordx4 v[96:99], v[0:1], off offset:3072
	global_load_dwordx4 v[100:103], v[0:1], off offset:2048
	global_load_dwordx4 v[104:107], v[0:1], off offset:1024
	global_load_dwordx4 v[108:111], v[0:1], off
	s_mov_b64 s[8:9], 0
	v_mov_b32_e32 v116, v231
	v_mov_b32_e32 v117, v138
	s_branch .LBB0_315

.LBB0_315:
	s_waitcnt vmcnt(0)
	v_mfma_f32_32x32x16_f16 v[16:31], v[32:35], v[108:111], 0
	v_add_u32_e32 v118, 64, v117
	v_cmp_le_i32_e32 vcc, v116, v238
	v_mfma_f32_32x32x16_f16 v[0:15], v[64:67], v[108:111], 0
	v_mfma_f32_32x32x16_f16 v[16:31], v[36:39], v[104:107], v[16:31]
	v_mfma_f32_32x32x16_f16 v[0:15], v[68:71], v[104:107], v[0:15]
	v_min_i32_e32 v104, s18, v118
	v_ashrrev_i32_e32 v105, 31, v104
	v_lshlrev_b64 v[104:105], 12, v[104:105]
	v_lshl_add_u64 v[112:113], v[154:155], 0, v[104:105]
	global_load_dwordx4 v[108:111], v[112:113], off
	global_load_dwordx4 v[104:107], v[112:113], off offset:1024
	v_mfma_f32_32x32x16_f16 v[16:31], v[40:43], v[100:103], v[16:31]
	v_mfma_f32_32x32x16_f16 v[0:15], v[72:75], v[100:103], v[0:15]
	global_load_dwordx4 v[100:103], v[112:113], off offset:2048
	s_nop 0
	global_load_dwordx4 v[112:115], v[112:113], off offset:3072
	v_mfma_f32_32x32x16_f16 v[16:31], v[44:47], v[96:99], v[16:31]
	v_mfma_f32_32x32x16_f16 v[0:15], v[76:79], v[96:99], v[0:15]
	s_and_saveexec_b64 s[4:5], vcc
	s_cbranch_execz .LBB0_319
	s_nop 8
	v_max_i32_e32 v16, 0, v16
	v_max_i32_e32 v17, 0, v17
	v_fma_f32 v16, v48, v16, 0
	v_max_i32_e32 v20, 0, v20
	v_fmac_f32_e32 v16, v49, v17
	v_max_i32_e32 v21, 0, v21
	v_fmac_f32_e32 v16, v50, v20
	v_max_i32_e32 v24, 0, v24
	v_fmac_f32_e32 v16, v51, v21
	v_max_i32_e32 v25, 0, v25
	v_fmac_f32_e32 v16, v52, v24
	v_max_i32_e32 v28, 0, v28
	v_fmac_f32_e32 v16, v53, v25
	v_max_i32_e32 v29, 0, v29
	v_fmac_f32_e32 v16, v54, v28
	v_fmac_f32_e32 v16, v55, v29
	v_bfe_u32 v17, v16, 19, 12
	s_movk_i32 s6, 0x5f0
	v_sub_u32_e64 v17, v17, s6 clamp
	v_min_u32_e32 v17, 0x3ff, v17
	v_xor_b32_e32 v20, 0x3ff, v17
	v_or_b32_e32 v17, 0x400, v17
	v_cmp_gt_i32_e32 vcc, 0, v16
	s_nop 1
	v_cndmask_b32_e32 v16, v17, v20, vcc
	v_lshlrev_b32_e32 v17, 1, v16
	v_and_b32_e32 v17, 0xffc, v17
	v_lshlrev_b32_e32 v16, 4, v16
	v_add_u32_e32 v17, v139, v17
	v_lshlrev_b32_e64 v16, v16, 1
	ds_add_u32 v17, v16
	s_or_b64 exec, exec, s[4:5]
	v_cmp_le_i32_e32 vcc, v116, v239
	s_and_saveexec_b64 s[4:5], vcc
	s_cbranch_execnz .LBB0_320

.LBB0_323:
	s_or_b64 exec, exec, s[4:5]
	s_waitcnt vmcnt(3)
	v_mfma_f32_32x32x16_f16 v[16:31], v[32:35], v[108:111], 0
	v_add_u32_e32 v117, 0x80, v117
	v_min_i32_e32 v96, s18, v117
	v_ashrrev_i32_e32 v97, 31, v96
	v_lshlrev_b64 v[96:97], 12, v[96:97]
	v_lshl_add_u64 v[96:97], v[154:155], 0, v[96:97]
	v_add_u32_e32 v119, 0x800, v116
	v_cmp_ge_i32_e64 s[4:5], s18, v118
	v_mfma_f32_32x32x16_f16 v[0:15], v[64:67], v[108:111], 0
	v_cmp_le_i32_e64 s[6:7], v119, v238
	v_cmp_lt_i32_e32 vcc, s18, v118
	s_and_b64 s[4:5], s[4:5], s[6:7]
	s_waitcnt vmcnt(2)
	v_mfma_f32_32x32x16_f16 v[16:31], v[36:39], v[104:107], v[16:31]
	v_mfma_f32_32x32x16_f16 v[0:15], v[68:71], v[104:107], v[0:15]
	global_load_dwordx4 v[108:111], v[96:97], off
	global_load_dwordx4 v[104:107], v[96:97], off offset:1024
	s_waitcnt vmcnt(3)
	v_mfma_f32_32x32x16_f16 v[16:31], v[40:43], v[100:103], v[16:31]
	v_mfma_f32_32x32x16_f16 v[0:15], v[72:75], v[100:103], v[0:15]
	global_load_dwordx4 v[100:103], v[96:97], off offset:2048
	s_nop 0
	global_load_dwordx4 v[96:99], v[96:97], off offset:3072
	s_waitcnt vmcnt(4)
	v_mfma_f32_32x32x16_f16 v[16:31], v[44:47], v[112:115], v[16:31]
	v_mfma_f32_32x32x16_f16 v[0:15], v[76:79], v[112:115], v[0:15]
	s_and_saveexec_b64 s[6:7], s[4:5]
	s_cbranch_execz .LBB0_325
	s_nop 8
	v_max_i32_e32 v16, 0, v16
	v_max_i32_e32 v17, 0, v17
	v_fma_f32 v16, v48, v16, 0
	v_max_i32_e32 v20, 0, v20
	v_fmac_f32_e32 v16, v49, v17
	v_max_i32_e32 v21, 0, v21
	v_fmac_f32_e32 v16, v50, v20
	v_max_i32_e32 v24, 0, v24
	v_fmac_f32_e32 v16, v51, v21
	v_max_i32_e32 v25, 0, v25
	v_fmac_f32_e32 v16, v52, v24
	v_max_i32_e32 v28, 0, v28
	v_fmac_f32_e32 v16, v53, v25
	v_max_i32_e32 v29, 0, v29
	v_fmac_f32_e32 v16, v54, v28
	v_fmac_f32_e32 v16, v55, v29
	v_bfe_u32 v17, v16, 19, 12
	s_movk_i32 s4, 0x5f0
	v_sub_u32_e64 v17, v17, s4 clamp
	v_min_u32_e32 v17, 0x3ff, v17
	v_xor_b32_e32 v20, 0x3ff, v17
	v_or_b32_e32 v17, 0x400, v17
	v_cmp_gt_i32_e64 s[4:5], 0, v16
	s_nop 1
	v_cndmask_b32_e64 v16, v17, v20, s[4:5]
	v_lshlrev_b32_e32 v17, 1, v16
	v_and_b32_e32 v17, 0xffc, v17
	v_lshlrev_b32_e32 v16, 4, v16
	v_add_u32_e32 v17, v139, v17
	v_lshlrev_b32_e64 v16, v16, 1
	ds_add_u32 v17, v16

.LBB0_343:
	v_cmp_ge_i32_e64 s[74:75], s18, v132
	v_add_u32_e32 v242, 0xe000, v160
	s_and_saveexec_b64 s[2:3], s[74:75]
	s_cbranch_execz .LBB0_370
	v_lshl_add_u64 v[0:1], v[154:155], 0, v[144:145]
	global_load_dwordx4 v[100:103], v[0:1], off offset:3072
	global_load_dwordx4 v[104:107], v[0:1], off offset:2048
	global_load_dwordx4 v[108:111], v[0:1], off offset:1024
	global_load_dwordx4 v[112:115], v[0:1], off
	ds_read2_b64 v[96:99], v242 offset0:32 offset1:34
	s_mov_b64 s[8:9], 0
	v_mov_b32_e32 v30, v232
	v_mov_b32_e32 v31, v132
	s_branch .LBB0_346

.LBB0_346:
	v_add_u32_e32 v243, 4, v31
	v_min_i32_e32 v0, s18, v243
	v_ashrrev_i32_e32 v1, 31, v0
	v_lshlrev_b64 v[0:1], 12, v[0:1]
	v_lshl_add_u64 v[0:1], v[154:155], 0, v[0:1]
	global_load_dwordx4 v[128:131], v[0:1], off
	global_load_dwordx4 v[116:119], v[0:1], off offset:1024
	global_load_dwordx4 v[120:123], v[0:1], off offset:2048
	global_load_dwordx4 v[124:127], v[0:1], off offset:3072
	s_waitcnt vmcnt(4)
	v_mfma_f32_32x32x16_f16 v[14:29], v[32:35], v[112:115], 0
	s_brev_b32 s4, 1
	v_cmp_le_i32_e32 vcc, v30, v238
	v_mfma_f32_32x32x16_f16 v[14:29], v[36:39], v[108:111], v[14:29]
	v_mfma_f32_32x32x16_f16 v[14:29], v[40:43], v[104:107], v[14:29]
	v_mfma_f32_32x32x16_f16 v[14:29], v[44:47], v[100:103], v[14:29]
	s_nop 11
	v_max_i32_e32 v0, 0, v14
	v_fma_f32 v244, v48, v0, 0
	v_max_i32_e32 v0, 0, v15
	v_fmac_f32_e32 v244, v49, v0
	v_max_i32_e32 v0, 0, v18
	v_fmac_f32_e32 v244, v50, v0
	v_max_i32_e32 v0, 0, v19
	v_fmac_f32_e32 v244, v51, v0
	v_max_i32_e32 v0, 0, v22
	v_fmac_f32_e32 v244, v52, v0
	v_max_i32_e32 v0, 0, v23
	v_fmac_f32_e32 v244, v53, v0
	v_max_i32_e32 v0, 0, v26
	v_fmac_f32_e32 v244, v54, v0
	v_max_i32_e32 v0, 0, v27
	v_fmac_f32_e32 v244, v55, v0
	v_mfma_f32_32x32x16_f16 v[0:15], v[64:67], v[112:115], 0
	v_ashrrev_i32_e32 v18, 31, v244
	v_bitop3_b32 v18, v18, v244, s4 bitop3:0x36
	s_waitcnt lgkmcnt(0)
	v_cmp_ge_u32_e64 s[4:5], v18, v96
	s_and_b64 s[6:7], vcc, s[4:5]
	v_mfma_f32_32x32x16_f16 v[0:15], v[68:71], v[108:111], v[0:15]
	v_mfma_f32_32x32x16_f16 v[0:15], v[72:75], v[104:107], v[0:15]
	v_mfma_f32_32x32x16_f16 v[0:15], v[76:79], v[100:103], v[0:15]
	s_and_saveexec_b64 s[4:5], s[6:7]
	s_cbranch_execz .LBB0_349
	v_add_u32_e32 v19, v139, v133
	ds_add_rtn_u32 v19, v19, v195 offset:57696
	s_movk_i32 s6, 0x400
	s_waitcnt lgkmcnt(0)
	v_cmp_gt_i32_e32 vcc, s6, v19
	s_and_b64 exec, exec, vcc
	s_cbranch_execz .LBB0_349
	v_lshl_add_u32 v22, v19, 2, v139
	v_add_lshl_u32 v19, v19, v173, 1
	v_sub_u32_e32 v19, v22, v19
	ds_write_b32 v22, v18
	ds_write_b16 v19, v30 offset:32768

.LBB0_358:
	s_or_b64 exec, exec, s[4:5]
	v_add_u32_e32 v31, 8, v31
	v_min_i32_e32 v0, s18, v31
	v_ashrrev_i32_e32 v1, 31, v0
	v_lshlrev_b64 v[0:1], 12, v[0:1]
	v_lshl_add_u64 v[0:1], v[154:155], 0, v[0:1]
	global_load_dwordx4 v[112:115], v[0:1], off
	global_load_dwordx4 v[108:111], v[0:1], off offset:1024
	global_load_dwordx4 v[104:107], v[0:1], off offset:2048
	global_load_dwordx4 v[100:103], v[0:1], off offset:3072
	s_waitcnt vmcnt(7)
	v_mfma_f32_32x32x16_f16 v[14:29], v[32:35], v[128:131], 0
	s_brev_b32 s6, 1
	v_cmp_ge_i32_e64 s[4:5], s18, v243
	v_cmp_lt_i32_e32 vcc, s18, v243
	s_waitcnt vmcnt(6)
	v_mfma_f32_32x32x16_f16 v[14:29], v[36:39], v[116:119], v[14:29]
	s_waitcnt vmcnt(5)
	v_mfma_f32_32x32x16_f16 v[14:29], v[40:43], v[120:123], v[14:29]
	s_waitcnt vmcnt(4)
	v_mfma_f32_32x32x16_f16 v[14:29], v[44:47], v[124:127], v[14:29]
	s_nop 11
	v_max_i32_e32 v0, 0, v14
	v_fma_f32 v244, v48, v0, 0
	v_max_i32_e32 v0, 0, v15
	v_fmac_f32_e32 v244, v49, v0
	v_max_i32_e32 v0, 0, v18
	v_fmac_f32_e32 v244, v50, v0
	v_max_i32_e32 v0, 0, v19
	v_fmac_f32_e32 v244, v51, v0
	v_max_i32_e32 v0, 0, v22
	v_fmac_f32_e32 v244, v52, v0
	v_max_i32_e32 v0, 0, v23
	v_fmac_f32_e32 v244, v53, v0
	v_max_i32_e32 v0, 0, v26
	v_fmac_f32_e32 v244, v54, v0
	v_max_i32_e32 v0, 0, v27
	v_fmac_f32_e32 v244, v55, v0
	v_mfma_f32_32x32x16_f16 v[0:15], v[64:67], v[128:131], 0
	v_add_u32_e32 v18, 0x80, v30
	v_ashrrev_i32_e32 v19, 31, v244
	v_bitop3_b32 v19, v19, v244, s6 bitop3:0x36
	v_cmp_le_i32_e64 s[6:7], v18, v238
	s_and_b64 s[6:7], s[4:5], s[6:7]
	v_cmp_ge_u32_e64 s[4:5], v19, v96
	s_and_b64 s[4:5], s[6:7], s[4:5]
	v_mfma_f32_32x32x16_f16 v[0:15], v[68:71], v[116:119], v[0:15]
	v_mfma_f32_32x32x16_f16 v[0:15], v[72:75], v[120:123], v[0:15]
	v_mfma_f32_32x32x16_f16 v[0:15], v[76:79], v[124:127], v[0:15]
	s_and_saveexec_b64 s[6:7], s[4:5]
	s_cbranch_execz .LBB0_361
	v_add_u32_e32 v22, v139, v133
	ds_add_rtn_u32 v22, v22, v195 offset:57696
	s_movk_i32 s4, 0x400
	s_waitcnt lgkmcnt(0)
	v_cmp_gt_i32_e64 s[4:5], s4, v22
	s_and_b64 exec, exec, s[4:5]
	s_cbranch_execz .LBB0_361
	v_lshl_add_u32 v23, v22, 2, v139
	v_add_lshl_u32 v22, v22, v173, 1
	v_sub_u32_e32 v22, v23, v22
	ds_write_b32 v23, v19
	ds_write_b16 v22, v18 offset:32768

.LBB0_388:
	global_load_dwordx4 v[0:3], v[102:103], off
	global_load_dwordx4 v[110:113], v[102:103], off offset:1024
	v_cmp_le_i32_e32 vcc, v106, v238
	s_waitcnt vmcnt(1)
	v_mfma_f32_32x32x16_f16 v[16:31], v[32:35], v[0:3], 0
	v_mfma_f32_32x32x16_f16 v[0:15], v[64:67], v[0:3], 0
	s_waitcnt vmcnt(0)
	v_mfma_f32_32x32x16_f16 v[16:31], v[36:39], v[110:113], v[16:31]
	v_mfma_f32_32x32x16_f16 v[0:15], v[68:71], v[110:113], v[0:15]
	global_load_dwordx4 v[110:113], v[102:103], off offset:2048
	s_waitcnt vmcnt(0)
	v_mfma_f32_32x32x16_f16 v[16:31], v[40:43], v[110:113], v[16:31]
	v_mfma_f32_32x32x16_f16 v[0:15], v[72:75], v[110:113], v[0:15]
	global_load_dwordx4 v[110:113], v[102:103], off offset:3072
	s_waitcnt vmcnt(0)
	v_mfma_f32_32x32x16_f16 v[16:31], v[44:47], v[110:113], v[16:31]
	v_mfma_f32_32x32x16_f16 v[0:15], v[76:79], v[110:113], v[0:15]
	s_and_saveexec_b64 s[4:5], vcc
	s_cbranch_execz .LBB0_400
	s_nop 8
	v_max_i32_e32 v16, 0, v16
	v_max_i32_e32 v110, 0, v17
	v_fma_f32 v17, v48, v16, 0
	v_max_i32_e32 v20, 0, v20
	v_fmac_f32_e32 v17, v49, v110
	v_max_i32_e32 v21, 0, v21
	v_fmac_f32_e32 v17, v50, v20
	v_max_i32_e32 v24, 0, v24
	v_fmac_f32_e32 v17, v51, v21
	v_max_i32_e32 v25, 0, v25
	v_fmac_f32_e32 v17, v52, v24
	v_max_i32_e32 v28, 0, v28
	v_fmac_f32_e32 v17, v53, v25
	v_max_i32_e32 v29, 0, v29
	v_fmac_f32_e32 v17, v54, v28
	v_fmac_f32_e32 v17, v55, v29
	v_bfe_u32 v16, v17, 19, 12
	s_movk_i32 s12, 0x5f0
	v_sub_u32_e64 v16, v16, s12 clamp
	v_min_u32_e32 v16, 0x3ff, v16
	v_xor_b32_e32 v20, 0x3ff, v16
	v_or_b32_e32 v16, 0x400, v16
	v_cmp_gt_i32_e32 vcc, 0, v17
	s_mov_b64 s[12:13], -1
	s_nop 0
	v_cndmask_b32_e32 v16, v16, v20, vcc
	s_and_b64 vcc, exec, s[8:9]
	s_cbranch_vccz .LBB0_398
	s_waitcnt lgkmcnt(0)
	v_cmp_le_i32_e32 vcc, v16, v96
	s_and_saveexec_b64 s[12:13], vcc
	s_xor_b64 s[12:13], exec, s[12:13]
	s_cbranch_execz .LBB0_395
	v_cmp_eq_u32_e32 vcc, v16, v96
	s_and_saveexec_b64 s[14:15], vcc
	s_cbranch_execz .LBB0_394
	v_add_u32_e32 v20, v139, v133
	ds_add_rtn_u32 v20, v20, v195 offset:57696
	s_movk_i32 s16, 0x400
	s_waitcnt lgkmcnt(0)
	v_cmp_gt_i32_e32 vcc, s16, v20
	s_and_b64 exec, exec, vcc
	s_cbranch_execz .LBB0_394
	v_add_lshl_u32 v20, v20, v173, 1
	v_ashrrev_i32_e32 v24, 31, v17
	s_brev_b32 s16, 1
	v_add_u32_e32 v21, v20, v20
	v_bitop3_b32 v17, v24, v17, s16 bitop3:0x36
	ds_write_b32 v21, v17
	ds_write_b16 v20, v106 offset:32768

.LBB0_469:
	s_andn2_saveexec_b64 s[58:59], s[6:7]
	s_cbranch_execz .LBB0_463
	s_movk_i32 s4, 0xffc
	v_mad_u64_u32 v[0:1], s[4:5], v19, s4, v[0:1]
	v_mov_b32_e32 v1, 0
	v_mov_b32_e32 v3, 0
	s_and_saveexec_b64 s[4:5], vcc
	v_lshl_add_u32 v3, v156, 2, v0
	ds_read_b32 v3, v3
	s_or_b64 exec, exec, s[4:5]
	v_cmp_ge_i32_e64 s[4:5], v182, v18
	v_cmp_lt_i32_e32 vcc, v182, v18
	s_and_saveexec_b64 s[6:7], vcc
	v_lshl_add_u32 v1, v156, 2, v0
	ds_read_b32 v1, v1 offset:256
	s_or_b64 exec, exec, s[6:7]
	v_cmp_ge_i32_e64 s[74:75], v183, v18
	v_cmp_lt_i32_e32 vcc, v183, v18
	v_mov_b32_e32 v4, 0
	v_mov_b32_e32 v5, 0
	s_and_saveexec_b64 s[6:7], vcc
	v_lshl_add_u32 v5, v156, 2, v0
	ds_read_b32 v5, v5 offset:512
	s_or_b64 exec, exec, s[6:7]
	v_cmp_ge_i32_e64 s[76:77], v184, v18
	v_cmp_lt_i32_e32 vcc, v184, v18
	s_and_saveexec_b64 s[6:7], vcc
	v_lshl_add_u32 v4, v156, 2, v0
	ds_read_b32 v4, v4 offset:768
	s_or_b64 exec, exec, s[6:7]
	v_cmp_ge_i32_e64 s[78:79], v185, v18
	v_cmp_lt_i32_e32 vcc, v185, v18
	v_mov_b32_e32 v6, 0
	v_mov_b32_e32 v7, 0
	s_and_saveexec_b64 s[6:7], vcc
	v_lshl_add_u32 v7, v156, 2, v0
	ds_read_b32 v7, v7 offset:1024
	s_or_b64 exec, exec, s[6:7]
	v_cmp_ge_i32_e64 s[80:81], v186, v18
	v_cmp_lt_i32_e32 vcc, v186, v18
	s_and_saveexec_b64 s[6:7], vcc
	v_lshl_add_u32 v6, v156, 2, v0
	ds_read_b32 v6, v6 offset:1280
	s_or_b64 exec, exec, s[6:7]
	v_cmp_ge_i32_e64 s[82:83], v187, v18
	v_cmp_lt_i32_e32 vcc, v187, v18
	v_mov_b32_e32 v8, 0
	v_mov_b32_e32 v9, 0
	s_and_saveexec_b64 s[6:7], vcc
	v_lshl_add_u32 v9, v156, 2, v0
	ds_read_b32 v9, v9 offset:1536
	s_or_b64 exec, exec, s[6:7]
	v_cmp_ge_i32_e64 s[84:85], v188, v18
	v_cmp_lt_i32_e32 vcc, v188, v18
	s_and_saveexec_b64 s[6:7], vcc
	v_lshl_add_u32 v8, v156, 2, v0
	ds_read_b32 v8, v8 offset:1792
	s_or_b64 exec, exec, s[6:7]
	v_cmp_ge_i32_e64 s[86:87], v189, v18
	v_cmp_lt_i32_e32 vcc, v189, v18
	v_mov_b32_e32 v10, 0
	v_mov_b32_e32 v11, 0
	s_and_saveexec_b64 s[6:7], vcc
	v_lshl_add_u32 v11, v156, 2, v0
	ds_read_b32 v11, v11 offset:2048
	s_or_b64 exec, exec, s[6:7]
	v_cmp_ge_i32_e64 s[88:89], v190, v18
	v_cmp_lt_i32_e32 vcc, v190, v18
	s_and_saveexec_b64 s[6:7], vcc
	v_lshl_add_u32 v10, v156, 2, v0
	ds_read_b32 v10, v10 offset:2304
	s_or_b64 exec, exec, s[6:7]
	v_cmp_ge_i32_e64 s[90:91], v191, v18
	v_cmp_lt_i32_e32 vcc, v191, v18
	v_mov_b32_e32 v12, 0
	v_mov_b32_e32 v13, 0
	s_and_saveexec_b64 s[6:7], vcc
	v_lshl_add_u32 v13, v156, 2, v0
	ds_read_b32 v13, v13 offset:2560
	s_or_b64 exec, exec, s[6:7]
	v_cmp_ge_i32_e64 s[92:93], v219, v18
	v_cmp_lt_i32_e32 vcc, v219, v18
	s_and_saveexec_b64 s[6:7], vcc
	v_lshl_add_u32 v12, v156, 2, v0
	ds_read_b32 v12, v12 offset:2816
	s_or_b64 exec, exec, s[6:7]
	v_cmp_ge_i32_e64 s[94:95], v220, v18
	v_cmp_lt_i32_e32 vcc, v220, v18
	v_mov_b32_e32 v14, 0
	v_mov_b32_e32 v15, 0
	s_and_saveexec_b64 s[6:7], vcc
	v_lshl_add_u32 v15, v156, 2, v0
	ds_read_b32 v15, v15 offset:3072
	s_or_b64 exec, exec, s[6:7]
	v_cmp_ge_i32_e64 s[96:97], v221, v18
	v_cmp_lt_i32_e32 vcc, v221, v18
	s_and_saveexec_b64 s[6:7], vcc
	v_lshl_add_u32 v14, v156, 2, v0
	ds_read_b32 v14, v14 offset:3328
	s_or_b64 exec, exec, s[6:7]
	v_cmp_ge_i32_e64 s[6:7], v222, v18
	v_cmp_lt_i32_e32 vcc, v222, v18
	v_mov_b32_e32 v16, 0
	v_mov_b32_e32 v17, 0
	s_and_saveexec_b64 s[8:9], vcc
	v_lshl_add_u32 v17, v156, 2, v0
	ds_read_b32 v17, v17 offset:3584
	s_or_b64 exec, exec, s[8:9]
	v_cmp_ge_i32_e64 s[8:9], v223, v18
	v_cmp_lt_i32_e32 vcc, v223, v18
	s_and_saveexec_b64 s[12:13], vcc
	v_lshl_add_u32 v16, v156, 2, v0
	ds_read_b32 v16, v16 offset:3840
	s_or_b64 exec, exec, s[12:13]
	v_mov_b32_e32 v18, 0
	s_mov_b32 s60, 31
.LBB0_503:
	v_lshl_or_b32 v21, 1, s60, v18
	s_waitcnt lgkmcnt(0)
	v_cmp_ge_u32_e64 s[12:13], v3, v21
	v_cmp_ge_u32_e64 s[14:15], v1, v21
	v_cmp_ge_u32_e64 s[16:17], v5, v21
	v_cmp_ge_u32_e64 s[18:19], v4, v21
	v_cmp_ge_u32_e64 s[20:21], v7, v21
	v_cmp_ge_u32_e64 s[22:23], v6, v21
	v_cmp_ge_u32_e64 s[24:25], v9, v21
	v_cmp_ge_u32_e64 s[26:27], v8, v21
	v_cmp_ge_u32_e64 s[28:29], v11, v21
	v_cmp_ge_u32_e64 s[30:31], v10, v21
	v_cmp_ge_u32_e64 s[34:35], v13, v21
	v_cmp_ge_u32_e64 s[36:37], v12, v21
	v_cmp_ge_u32_e64 s[38:39], v15, v21
	v_cmp_ge_u32_e64 s[40:41], v14, v21
	v_cmp_ge_u32_e64 s[66:67], v17, v21
	v_cmp_ge_u32_e32 vcc, v16, v21
	s_bcnt1_i32_b64 s12, s[12:13]
	s_bcnt1_i32_b64 s14, s[14:15]
	s_bcnt1_i32_b64 s16, s[16:17]
	s_bcnt1_i32_b64 s18, s[18:19]
	s_bcnt1_i32_b64 s20, s[20:21]
	s_bcnt1_i32_b64 s22, s[22:23]
	s_bcnt1_i32_b64 s24, s[24:25]
	s_bcnt1_i32_b64 s26, s[26:27]
	s_bcnt1_i32_b64 s28, s[28:29]
	s_bcnt1_i32_b64 s30, s[30:31]
	s_bcnt1_i32_b64 s34, s[34:35]
	s_bcnt1_i32_b64 s36, s[36:37]
	s_bcnt1_i32_b64 s38, s[38:39]
	s_bcnt1_i32_b64 s40, s[40:41]
	s_bcnt1_i32_b64 s66, s[66:67]
	s_bcnt1_i32_b64 s61, vcc
	s_add_i32 s12, s12, s14
	s_add_i32 s16, s16, s18
	s_add_i32 s20, s20, s22
	s_add_i32 s24, s24, s26
	s_add_i32 s28, s28, s30
	s_add_i32 s34, s34, s36
	s_add_i32 s38, s38, s40
	s_add_i32 s66, s66, s61
	s_add_i32 s12, s12, s16
	s_add_i32 s20, s20, s24
	s_add_i32 s28, s28, s34
	s_add_i32 s38, s38, s66
	s_add_i32 s12, s12, s20
	s_add_i32 s28, s28, s38
	s_add_i32 s12, s12, s28
	s_add_i32 s60, s60, -1
	v_cmp_gt_i32_e32 vcc, s12, v20
	s_cmp_eq_u32 s60, -1
	s_nop 0
	v_cndmask_b32_e32 v18, v18, v21, vcc
	s_cbranch_scc0 .LBB0_503
	v_lshlrev_b32_e32 v20, 11, v19
	v_cmp_gt_u32_e32 vcc, v3, v18
	s_movk_i32 s56, 0x420
	s_xor_b64 s[62:63], s[10:11], -1
	v_sub_u32_e32 v20, v0, v20
	v_cmp_gt_u32_e64 s[12:13], v1, v18
	v_cmp_gt_u32_e64 s[14:15], v5, v18
	v_cmp_gt_u32_e64 s[16:17], v4, v18
	v_cmp_gt_u32_e64 s[18:19], v7, v18
	v_cmp_gt_u32_e64 s[20:21], v6, v18
	v_cmp_gt_u32_e64 s[22:23], v9, v18
	v_cmp_gt_u32_e64 s[24:25], v8, v18
	v_cmp_gt_u32_e64 s[26:27], v11, v18
	v_cmp_gt_u32_e64 s[28:29], v10, v18
	v_cmp_gt_u32_e64 s[30:31], v13, v18
	v_cmp_gt_u32_e64 s[34:35], v12, v18
	v_cmp_gt_u32_e64 s[36:37], v15, v18
	v_cmp_gt_u32_e64 s[38:39], v14, v18
	v_cmp_gt_u32_e64 s[40:41], v17, v18
	v_cmp_gt_u32_e64 s[66:67], v16, v18
	v_mul_lo_u32 v0, v19, s56
	s_and_b64 s[60:61], s[62:63], vcc
	s_and_saveexec_b64 s[10:11], s[60:61]
	s_cbranch_execz .LBB0_506
	v_lshl_add_u32 v19, v156, 1, v20
	ds_read_u16 v19, v19 offset:32768
	s_waitcnt lgkmcnt(0)
	v_lshrrev_b32_e32 v21, 3, v19
	v_and_b32_e32 v21, 0x1ffc, v21
	v_add_u32_e32 v21, v0, v21
	v_lshlrev_b32_e64 v19, v19, 1
	ds_or_b32 v21, v19 offset:49152

.LBB0_643:
	s_andn2_saveexec_b64 s[4:5], s[4:5]
	s_cbranch_execz .LBB0_645
	v_mov_b32_e32 v132, v125
	v_mov_b32_e32 v133, v126
	v_mov_b32_e32 v134, v124
	v_mov_b32_e32 v135, v127
	v_pk_add_f32 v[132:133], v[132:133], v[134:135]
	v_mov_b32_e32 v134, v121
	v_mov_b32_e32 v135, v122
	v_mov_b32_e32 v138, v120
	v_mov_b32_e32 v139, v123
	v_pk_add_f32 v[134:135], v[134:135], v[138:139]
	v_add_f32_e32 v132, v132, v133
	v_pk_add_f32 v[134:135], v[134:135], v[134:135] op_sel:[0,1] op_sel_hi:[1,0]
	v_add_f32_e32 v132, 0, v132
	v_add_f32_e32 v138, v116, v117
	s_waitcnt vmcnt(8)
	v_add_f32_e32 v140, v118, v119
	v_mov_b32_e32 v133, v112
	v_mov_b32_e32 v135, v113
	v_mov_b32_e32 v139, v114
	v_mov_b32_e32 v141, v115
	v_pk_add_f32 v[132:133], v[132:133], v[134:135]
	v_pk_add_f32 v[134:135], v[138:139], v[140:141]
	v_cmp_lt_i32_e32 vcc, v203, v201
	v_pk_add_f32 v[132:133], v[132:133], v[134:135]
	s_mov_b32 s21, 0x800000
	v_add_f32_e32 v132, v132, v133
	v_cndmask_b32_e32 v133, v199, v203, vcc
	v_lshlrev_b32_e32 v137, 2, v133
	ds_bpermute_b32 v133, v137, v132
	v_cmp_lt_i32_e32 vcc, v202, v201
	v_lshlrev_b32_e32 v176, 1, v129
	s_waitcnt lgkmcnt(0)
	v_add_f32_e32 v132, v132, v133
	v_cndmask_b32_e32 v133, v199, v202, vcc
	s_waitcnt vmcnt(2)
	v_lshlrev_b32_e32 v166, 2, v133
	ds_bpermute_b32 v133, v166, v132
	s_waitcnt lgkmcnt(0)
	v_add_f32_e32 v132, v132, v133
	v_mul_f32_e32 v132, 0x3c800000, v132
	v_pk_add_f32 v[144:145], v[124:125], v[132:133] op_sel_hi:[1,0] neg_lo:[0,1] neg_hi:[0,1]
	v_pk_add_f32 v[148:149], v[126:127], v[132:133] op_sel_hi:[1,0] neg_lo:[0,1] neg_hi:[0,1]
	v_pk_mul_f32 v[146:147], v[144:145], v[144:145]
	v_pk_mul_f32 v[150:151], v[148:149], v[148:149]
	v_add_f32_e32 v146, v146, v147
	v_pk_add_f32 v[152:153], v[120:121], v[132:133] op_sel_hi:[1,0] neg_lo:[0,1] neg_hi:[0,1]
	v_add_f32_e32 v146, v150, v146
	v_pk_mul_f32 v[154:155], v[152:153], v[152:153]
	v_add_f32_e32 v146, v151, v146
	v_pk_add_f32 v[156:157], v[122:123], v[132:133] op_sel_hi:[1,0] neg_lo:[0,1] neg_hi:[0,1]
	v_add_f32_e32 v146, v154, v146
	v_pk_mul_f32 v[158:159], v[156:157], v[156:157]
	v_add_f32_e32 v146, v155, v146
	v_pk_add_f32 v[160:161], v[116:117], v[132:133] op_sel_hi:[1,0] neg_lo:[0,1] neg_hi:[0,1]
	v_add_f32_e32 v146, v158, v146
	v_pk_mul_f32 v[162:163], v[160:161], v[160:161]
	v_add_f32_e32 v146, v159, v146
	v_pk_add_f32 v[134:135], v[112:113], v[132:133] op_sel_hi:[1,0] neg_lo:[0,1] neg_hi:[0,1]
	v_pk_add_f32 v[140:141], v[114:115], v[132:133] op_sel_hi:[1,0] neg_lo:[0,1] neg_hi:[0,1]
	v_pk_add_f32 v[132:133], v[118:119], v[132:133] op_sel_hi:[1,0] neg_lo:[0,1] neg_hi:[0,1]
	v_add_f32_e32 v146, v162, v146
	v_pk_mul_f32 v[164:165], v[132:133], v[132:133]
	v_add_f32_e32 v146, v163, v146
	v_add_f32_e32 v146, v164, v146
	v_pk_mul_f32 v[138:139], v[134:135], v[134:135]
	v_add_f32_e32 v146, v165, v146
	v_add_f32_e32 v138, v138, v146
	v_pk_mul_f32 v[142:143], v[140:141], v[140:141]
	v_add_f32_e32 v138, v139, v138
	v_add_f32_e32 v138, v142, v138
	v_add_f32_e32 v138, v143, v138
	ds_bpermute_b32 v137, v137, v138
	s_waitcnt lgkmcnt(0)
	v_add_f32_e32 v137, v138, v137
	ds_bpermute_b32 v142, v166, v137
	v_add_u32_e32 v138, 0x1ff0, v130
	v_lshrrev_b32_e32 v138, 14, v138
	v_mul_u32_u24_e32 v139, 0x2010, v138
	v_sub_u32_e32 v139, v130, v139
	v_min_u32_e32 v139, 0x205f, v139
	v_mul_u32_u24_e32 v138, 0x101000, v138
	v_lshl_add_u32 v138, v139, 7, v138
	v_and_b32_e32 v139, 31, v139
	v_mul_u32_u24_e32 v139, 0x70, v139
	v_sub_u32_e32 v138, v138, v139
	v_and_b32_e32 v139, 16, v176
	v_lshl_add_u32 v138, v139, 5, v138
	v_and_b32_e32 v139, 8, v176
	v_add_u32_e32 v138, v138, v139
	v_mov_b32_e32 v139, 0
	v_lshl_add_u64 v[138:139], s[8:9], 0, v[138:139]
	s_waitcnt lgkmcnt(0)
	v_add_f32_e32 v137, v137, v142
	v_fmamk_f32 v137, v137, 0x3c800000, v196
	v_mul_f32_e32 v142, 0x4b800000, v137
	v_cmp_gt_f32_e32 vcc, s21, v137
	s_nop 1
	v_cndmask_b32_e32 v137, v137, v142, vcc
	v_rsq_f32_e32 v137, v137
	s_nop 0
	v_mul_f32_e32 v142, 0x45800000, v137
	v_cndmask_b32_e32 v142, v137, v142, vcc
	v_pk_mul_f32 v[144:145], v[144:145], v[142:143] op_sel_hi:[1,0]
	v_pk_mul_f32 v[146:147], v[148:149], v[142:143] op_sel_hi:[1,0]
	v_cvt_pk_f16_f32 v144, v144, v145
	v_cvt_pk_f16_f32 v145, v146, v147
	global_store_dwordx2 v[138:139], v[144:145], off
	v_pk_mul_f32 v[144:145], v[152:153], v[142:143] op_sel_hi:[1,0]
	v_pk_mul_f32 v[146:147], v[156:157], v[142:143] op_sel_hi:[1,0]
	v_cvt_pk_f16_f32 v144, v144, v145
	v_cvt_pk_f16_f32 v145, v146, v147
	global_store_dwordx2 v[138:139], v[144:145], off offset:1024
	v_pk_mul_f32 v[144:145], v[160:161], v[142:143] op_sel_hi:[1,0]
	v_pk_mul_f32 v[132:133], v[132:133], v[142:143] op_sel_hi:[1,0]
	v_cvt_pk_f16_f32 v144, v144, v145
	v_cvt_pk_f16_f32 v145, v132, v133
	v_pk_mov_b32 v[132:133], v[134:135], v[140:141] op_sel:[1,0]
	v_fma_mixlo_f16 v137, v134, v142, 0
	v_pk_mul_f32 v[132:133], v[132:133], v[142:143] op_sel_hi:[1,0]
	v_fma_mixlo_f16 v134, v141, v142, 0
	v_cvt_pk_f16_f32 v133, v132, v133
	v_pack_b32_f16 v132, v137, v133
	v_alignbit_b32 v133, v134, v133, 16
	global_store_dwordx2 v[138:139], v[144:145], off offset:2048
	global_store_dwordx2 v[138:139], v[132:133], off offset:3072

.LBB0_655:
	s_andn2_saveexec_b64 s[26:27], s[26:27]
	s_cbranch_execz .LBB0_657
	v_mov_b32_e32 v138, v109
	v_mov_b32_e32 v139, v110
	s_waitcnt vmcnt(8)
	v_mov_b32_e32 v140, v108
	v_mov_b32_e32 v141, v111
	v_pk_add_f32 v[138:139], v[138:139], v[140:141]
	v_mov_b32_e32 v140, v105
	v_mov_b32_e32 v141, v106
	v_mov_b32_e32 v142, v104
	v_mov_b32_e32 v143, v107
	v_pk_add_f32 v[140:141], v[140:141], v[142:143]
	v_add_f32_e32 v131, v138, v139
	v_pk_add_f32 v[140:141], v[140:141], v[140:141] op_sel:[0,1] op_sel_hi:[1,0]
	v_add_f32_e32 v138, 0, v131
	v_add_f32_e32 v142, v100, v101
	s_waitcnt vmcnt(7)
	v_add_f32_e32 v144, v102, v103
	v_mov_b32_e32 v139, v96
	v_mov_b32_e32 v141, v97
	v_mov_b32_e32 v143, v98
	v_mov_b32_e32 v145, v99
	v_pk_add_f32 v[138:139], v[138:139], v[140:141]
	v_pk_add_f32 v[140:141], v[142:143], v[144:145]
	v_cmp_lt_i32_e32 vcc, v203, v201
	v_pk_add_f32 v[138:139], v[138:139], v[140:141]
	s_mov_b32 s21, 0x800000
	v_cndmask_b32_e32 v133, v199, v203, vcc
	v_add_f32_e32 v131, v138, v139
	v_lshlrev_b32_e32 v133, 2, v133
	ds_bpermute_b32 v137, v133, v131
	v_cmp_lt_i32_e32 vcc, v202, v201
	s_waitcnt lgkmcnt(0)
	v_add_f32_e32 v131, v131, v137
	v_cndmask_b32_e32 v137, v199, v202, vcc
	v_lshlrev_b32_e32 v137, 2, v137
	ds_bpermute_b32 v138, v137, v131
	s_waitcnt lgkmcnt(0)
	v_add_f32_e32 v131, v131, v138
	v_mul_f32_e32 v138, 0x3c800000, v131
	s_waitcnt vmcnt(6)
	v_pk_add_f32 v[148:149], v[108:109], v[138:139] op_sel_hi:[1,0] neg_lo:[0,1] neg_hi:[0,1]
	s_waitcnt vmcnt(5)
	v_pk_add_f32 v[152:153], v[110:111], v[138:139] op_sel_hi:[1,0] neg_lo:[0,1] neg_hi:[0,1]
	v_pk_mul_f32 v[150:151], v[148:149], v[148:149]
	v_pk_mul_f32 v[154:155], v[152:153], v[152:153]
	v_add_f32_e32 v131, v150, v151
	s_waitcnt vmcnt(4)
	v_pk_add_f32 v[156:157], v[104:105], v[138:139] op_sel_hi:[1,0] neg_lo:[0,1] neg_hi:[0,1]
	v_add_f32_e32 v131, v154, v131
	v_pk_mul_f32 v[158:159], v[156:157], v[156:157]
	v_add_f32_e32 v131, v155, v131
	s_waitcnt vmcnt(3)
	v_pk_add_f32 v[160:161], v[106:107], v[138:139] op_sel_hi:[1,0] neg_lo:[0,1] neg_hi:[0,1]
	v_add_f32_e32 v131, v158, v131
	v_pk_mul_f32 v[162:163], v[160:161], v[160:161]
	v_add_f32_e32 v131, v159, v131
	s_waitcnt vmcnt(2)
	v_pk_add_f32 v[164:165], v[100:101], v[138:139] op_sel_hi:[1,0] neg_lo:[0,1] neg_hi:[0,1]
	v_add_f32_e32 v131, v162, v131
	v_pk_mul_f32 v[166:167], v[164:165], v[164:165]
	v_add_f32_e32 v131, v163, v131
	v_pk_add_f32 v[140:141], v[96:97], v[138:139] op_sel_hi:[1,0] neg_lo:[0,1] neg_hi:[0,1]
	v_pk_add_f32 v[144:145], v[98:99], v[138:139] op_sel_hi:[1,0] neg_lo:[0,1] neg_hi:[0,1]
	v_pk_add_f32 v[138:139], v[102:103], v[138:139] op_sel_hi:[1,0] neg_lo:[0,1] neg_hi:[0,1]
	v_add_f32_e32 v131, v166, v131
	s_waitcnt vmcnt(1)
	v_pk_mul_f32 v[168:169], v[138:139], v[138:139]
	v_add_f32_e32 v131, v167, v131
	v_add_f32_e32 v131, v168, v131
	v_pk_mul_f32 v[142:143], v[140:141], v[140:141]
	v_add_f32_e32 v131, v169, v131
	v_add_f32_e32 v131, v142, v131
	v_pk_mul_f32 v[146:147], v[144:145], v[144:145]
	v_add_f32_e32 v131, v143, v131
	v_add_f32_e32 v131, v146, v131
	v_add_f32_e32 v131, v147, v131
	ds_bpermute_b32 v133, v133, v131
	v_lshlrev_b32_e32 v146, 1, v129
	v_mov_b32_e32 v147, v177
	s_waitcnt lgkmcnt(0)
	v_add_f32_e32 v131, v131, v133
	ds_bpermute_b32 v133, v137, v131
	v_add_u32_e32 v142, 0x1ff0, v134
	v_lshrrev_b32_e32 v142, 14, v142
	v_mul_u32_u24_e32 v143, 0x2010, v142
	v_sub_u32_e32 v143, v134, v143
	v_min_u32_e32 v143, 0x205f, v143
	v_mul_u32_u24_e32 v142, 0x101000, v142
	v_lshl_add_u32 v142, v143, 7, v142
	v_and_b32_e32 v143, 31, v143
	v_mul_u32_u24_e32 v143, 0x70, v143
	v_sub_u32_e32 v142, v142, v143
	v_and_b32_e32 v143, 16, v146
	v_lshl_add_u32 v142, v143, 5, v142
	v_and_b32_e32 v143, 8, v146
	v_add_u32_e32 v142, v142, v143
	v_mov_b32_e32 v143, 0
	v_lshl_add_u64 v[142:143], s[8:9], 0, v[142:143]
	s_waitcnt lgkmcnt(0)
	v_add_f32_e32 v131, v131, v133
	v_fmamk_f32 v131, v131, 0x3c800000, v196
	v_mul_f32_e32 v133, 0x4b800000, v131
	v_cmp_gt_f32_e32 vcc, s21, v131
	s_nop 1
	v_cndmask_b32_e32 v131, v131, v133, vcc
	v_rsq_f32_e32 v131, v131
	s_nop 0
	v_mul_f32_e32 v133, 0x45800000, v131
	v_cndmask_b32_e32 v146, v131, v133, vcc
	v_pk_mul_f32 v[148:149], v[148:149], v[146:147] op_sel_hi:[1,0]
	v_pk_mul_f32 v[150:151], v[152:153], v[146:147] op_sel_hi:[1,0]
	v_cvt_pk_f16_f32 v148, v148, v149
	v_cvt_pk_f16_f32 v149, v150, v151
	global_store_dwordx2 v[142:143], v[148:149], off
	v_pk_mul_f32 v[148:149], v[156:157], v[146:147] op_sel_hi:[1,0]
	v_pk_mul_f32 v[150:151], v[160:161], v[146:147] op_sel_hi:[1,0]
	v_cvt_pk_f16_f32 v148, v148, v149
	v_cvt_pk_f16_f32 v149, v150, v151
	global_store_dwordx2 v[142:143], v[148:149], off offset:1024
	v_pk_mul_f32 v[148:149], v[164:165], v[146:147] op_sel_hi:[1,0]
	v_pk_mul_f32 v[138:139], v[138:139], v[146:147] op_sel_hi:[1,0]
	v_cvt_pk_f16_f32 v148, v148, v149
	v_cvt_pk_f16_f32 v149, v138, v139
	v_pk_mov_b32 v[138:139], v[140:141], v[144:145] op_sel:[1,0]
	v_fma_mixlo_f16 v131, v140, v146, 0
	v_pk_mul_f32 v[138:139], v[138:139], v[146:147] op_sel_hi:[1,0]
	global_store_dwordx2 v[142:143], v[148:149], off offset:2048
	v_cvt_pk_f16_f32 v133, v138, v139
	v_pack_b32_f16 v138, v131, v133
	v_fma_mixlo_f16 v131, v145, v146, 0
	v_alignbit_b32 v139, v131, v133, 16
	global_store_dwordx2 v[142:143], v[138:139], off offset:3072

.LBB0_667:
	s_andn2_saveexec_b64 s[26:27], s[26:27]
	s_cbranch_execz .LBB0_669
	v_mov_b32_e32 v138, v93
	v_mov_b32_e32 v139, v94
	s_waitcnt vmcnt(8)
	v_mov_b32_e32 v140, v92
	v_mov_b32_e32 v141, v95
	v_pk_add_f32 v[138:139], v[138:139], v[140:141]
	v_mov_b32_e32 v140, v89
	v_mov_b32_e32 v141, v90
	v_mov_b32_e32 v142, v88
	v_mov_b32_e32 v143, v91
	v_pk_add_f32 v[140:141], v[140:141], v[142:143]
	v_add_f32_e32 v131, v138, v139
	v_pk_add_f32 v[140:141], v[140:141], v[140:141] op_sel:[0,1] op_sel_hi:[1,0]
	v_add_f32_e32 v138, 0, v131
	v_add_f32_e32 v142, v84, v85
	s_waitcnt vmcnt(7)
	v_add_f32_e32 v144, v86, v87
	v_mov_b32_e32 v139, v80
	v_mov_b32_e32 v141, v81
	v_mov_b32_e32 v143, v82
	v_mov_b32_e32 v145, v83
	v_pk_add_f32 v[138:139], v[138:139], v[140:141]
	v_pk_add_f32 v[140:141], v[142:143], v[144:145]
	v_cmp_lt_i32_e32 vcc, v203, v201
	v_pk_add_f32 v[138:139], v[138:139], v[140:141]
	s_mov_b32 s21, 0x800000
	v_cndmask_b32_e32 v133, v199, v203, vcc
	v_add_f32_e32 v131, v138, v139
	v_lshlrev_b32_e32 v133, 2, v133
	ds_bpermute_b32 v137, v133, v131
	v_cmp_lt_i32_e32 vcc, v202, v201
	s_waitcnt lgkmcnt(0)
	v_add_f32_e32 v131, v131, v137
	v_cndmask_b32_e32 v137, v199, v202, vcc
	v_lshlrev_b32_e32 v137, 2, v137
	ds_bpermute_b32 v138, v137, v131
	s_waitcnt lgkmcnt(0)
	v_add_f32_e32 v131, v131, v138
	v_mul_f32_e32 v138, 0x3c800000, v131
	s_waitcnt vmcnt(6)
	v_pk_add_f32 v[148:149], v[92:93], v[138:139] op_sel_hi:[1,0] neg_lo:[0,1] neg_hi:[0,1]
	s_waitcnt vmcnt(5)
	v_pk_add_f32 v[152:153], v[94:95], v[138:139] op_sel_hi:[1,0] neg_lo:[0,1] neg_hi:[0,1]
	v_pk_mul_f32 v[150:151], v[148:149], v[148:149]
	v_pk_mul_f32 v[154:155], v[152:153], v[152:153]
	v_add_f32_e32 v131, v150, v151
	s_waitcnt vmcnt(4)
	v_pk_add_f32 v[156:157], v[88:89], v[138:139] op_sel_hi:[1,0] neg_lo:[0,1] neg_hi:[0,1]
	v_add_f32_e32 v131, v154, v131
	v_pk_mul_f32 v[158:159], v[156:157], v[156:157]
	v_add_f32_e32 v131, v155, v131
	s_waitcnt vmcnt(3)
	v_pk_add_f32 v[160:161], v[90:91], v[138:139] op_sel_hi:[1,0] neg_lo:[0,1] neg_hi:[0,1]
	v_add_f32_e32 v131, v158, v131
	v_pk_mul_f32 v[162:163], v[160:161], v[160:161]
	v_add_f32_e32 v131, v159, v131
	s_waitcnt vmcnt(2)
	v_pk_add_f32 v[164:165], v[84:85], v[138:139] op_sel_hi:[1,0] neg_lo:[0,1] neg_hi:[0,1]
	v_add_f32_e32 v131, v162, v131
	v_pk_mul_f32 v[166:167], v[164:165], v[164:165]
	v_add_f32_e32 v131, v163, v131
	v_pk_add_f32 v[140:141], v[80:81], v[138:139] op_sel_hi:[1,0] neg_lo:[0,1] neg_hi:[0,1]
	v_pk_add_f32 v[144:145], v[82:83], v[138:139] op_sel_hi:[1,0] neg_lo:[0,1] neg_hi:[0,1]
	v_pk_add_f32 v[138:139], v[86:87], v[138:139] op_sel_hi:[1,0] neg_lo:[0,1] neg_hi:[0,1]
	v_add_f32_e32 v131, v166, v131
	s_waitcnt vmcnt(1)
	v_pk_mul_f32 v[168:169], v[138:139], v[138:139]
	v_add_f32_e32 v131, v167, v131
	v_add_f32_e32 v131, v168, v131
	v_pk_mul_f32 v[142:143], v[140:141], v[140:141]
	v_add_f32_e32 v131, v169, v131
	v_add_f32_e32 v131, v142, v131
	v_pk_mul_f32 v[146:147], v[144:145], v[144:145]
	v_add_f32_e32 v131, v143, v131
	v_add_f32_e32 v131, v146, v131
	v_add_f32_e32 v131, v147, v131
	ds_bpermute_b32 v133, v133, v131
	v_lshlrev_b32_e32 v146, 1, v129
	v_mov_b32_e32 v147, v177
	s_waitcnt lgkmcnt(0)
	v_add_f32_e32 v131, v131, v133
	ds_bpermute_b32 v133, v137, v131
	v_add_u32_e32 v142, 0x1ff0, v134
	v_lshrrev_b32_e32 v142, 14, v142
	v_mul_u32_u24_e32 v143, 0x2010, v142
	v_sub_u32_e32 v143, v134, v143
	v_min_u32_e32 v143, 0x205f, v143
	v_mul_u32_u24_e32 v142, 0x101000, v142
	v_lshl_add_u32 v142, v143, 7, v142
	v_and_b32_e32 v143, 31, v143
	v_mul_u32_u24_e32 v143, 0x70, v143
	v_sub_u32_e32 v142, v142, v143
	v_and_b32_e32 v143, 16, v146
	v_lshl_add_u32 v142, v143, 5, v142
	v_and_b32_e32 v143, 8, v146
	v_add_u32_e32 v142, v142, v143
	v_mov_b32_e32 v143, 0
	v_lshl_add_u64 v[142:143], s[8:9], 0, v[142:143]
	s_waitcnt lgkmcnt(0)
	v_add_f32_e32 v131, v131, v133
	v_fmamk_f32 v131, v131, 0x3c800000, v196
	v_mul_f32_e32 v133, 0x4b800000, v131
	v_cmp_gt_f32_e32 vcc, s21, v131
	s_nop 1
	v_cndmask_b32_e32 v131, v131, v133, vcc
	v_rsq_f32_e32 v131, v131
	s_nop 0
	v_mul_f32_e32 v133, 0x45800000, v131
	v_cndmask_b32_e32 v146, v131, v133, vcc
	v_pk_mul_f32 v[148:149], v[148:149], v[146:147] op_sel_hi:[1,0]
	v_pk_mul_f32 v[150:151], v[152:153], v[146:147] op_sel_hi:[1,0]
	v_cvt_pk_f16_f32 v148, v148, v149
	v_cvt_pk_f16_f32 v149, v150, v151
	global_store_dwordx2 v[142:143], v[148:149], off
	v_pk_mul_f32 v[148:149], v[156:157], v[146:147] op_sel_hi:[1,0]
	v_pk_mul_f32 v[150:151], v[160:161], v[146:147] op_sel_hi:[1,0]
	v_cvt_pk_f16_f32 v148, v148, v149
	v_cvt_pk_f16_f32 v149, v150, v151
	global_store_dwordx2 v[142:143], v[148:149], off offset:1024
	v_pk_mul_f32 v[148:149], v[164:165], v[146:147] op_sel_hi:[1,0]
	v_pk_mul_f32 v[138:139], v[138:139], v[146:147] op_sel_hi:[1,0]
	v_cvt_pk_f16_f32 v148, v148, v149
	v_cvt_pk_f16_f32 v149, v138, v139
	v_pk_mov_b32 v[138:139], v[140:141], v[144:145] op_sel:[1,0]
	v_fma_mixlo_f16 v131, v140, v146, 0
	v_pk_mul_f32 v[138:139], v[138:139], v[146:147] op_sel_hi:[1,0]
	global_store_dwordx2 v[142:143], v[148:149], off offset:2048
	v_cvt_pk_f16_f32 v133, v138, v139
	v_pack_b32_f16 v138, v131, v133
	v_fma_mixlo_f16 v131, v145, v146, 0
	v_alignbit_b32 v139, v131, v133, 16
	global_store_dwordx2 v[142:143], v[138:139], off offset:3072

.LBB0_679:
	s_andn2_saveexec_b64 s[0:1], s[0:1]
	s_cbranch_execz .LBB0_681
	v_mov_b32_e32 v134, v77
	v_mov_b32_e32 v135, v78
	v_mov_b32_e32 v138, v76
	v_mov_b32_e32 v139, v79
	v_pk_add_f32 v[134:135], v[134:135], v[138:139]
	v_mov_b32_e32 v138, v73
	v_mov_b32_e32 v139, v74
	s_waitcnt vmcnt(8)
	v_mov_b32_e32 v140, v72
	v_mov_b32_e32 v141, v75
	v_pk_add_f32 v[138:139], v[138:139], v[140:141]
	v_add_f32_e32 v133, v134, v135
	v_pk_add_f32 v[138:139], v[138:139], v[138:139] op_sel:[0,1] op_sel_hi:[1,0]
	v_add_f32_e32 v134, 0, v133
	v_add_f32_e32 v140, v68, v69
	v_add_f32_e32 v142, v70, v71
	v_mov_b32_e32 v135, v64
	v_mov_b32_e32 v139, v65
	v_mov_b32_e32 v141, v66
	v_mov_b32_e32 v143, v67
	v_pk_add_f32 v[134:135], v[134:135], v[138:139]
	v_pk_add_f32 v[138:139], v[140:141], v[142:143]
	v_cmp_lt_i32_e32 vcc, v203, v201
	v_pk_add_f32 v[134:135], v[134:135], v[138:139]
	s_mov_b32 s4, 0x800000
	v_add_f32_e32 v133, v134, v135
	v_cndmask_b32_e32 v134, v199, v203, vcc
	v_lshlrev_b32_e32 v137, 2, v134
	ds_bpermute_b32 v134, v137, v133
	v_cmp_lt_i32_e32 vcc, v202, v201
	s_waitcnt lgkmcnt(0)
	v_add_f32_e32 v133, v133, v134
	v_cndmask_b32_e32 v134, v199, v202, vcc
	s_waitcnt vmcnt(1)
	v_lshlrev_b32_e32 v168, 2, v134
	ds_bpermute_b32 v134, v168, v133
	s_waitcnt lgkmcnt(0)
	v_add_f32_e32 v133, v133, v134
	v_mul_f32_e32 v134, 0x3c800000, v133
	v_pk_add_f32 v[146:147], v[76:77], v[134:135] op_sel_hi:[1,0] neg_lo:[0,1] neg_hi:[0,1]
	v_pk_add_f32 v[150:151], v[78:79], v[134:135] op_sel_hi:[1,0] neg_lo:[0,1] neg_hi:[0,1]
	v_pk_mul_f32 v[148:149], v[146:147], v[146:147]
	v_pk_mul_f32 v[152:153], v[150:151], v[150:151]
	v_add_f32_e32 v133, v148, v149
	v_pk_add_f32 v[154:155], v[72:73], v[134:135] op_sel_hi:[1,0] neg_lo:[0,1] neg_hi:[0,1]
	v_add_f32_e32 v133, v152, v133
	v_pk_mul_f32 v[156:157], v[154:155], v[154:155]
	v_add_f32_e32 v133, v153, v133
	v_pk_add_f32 v[158:159], v[74:75], v[134:135] op_sel_hi:[1,0] neg_lo:[0,1] neg_hi:[0,1]
	v_add_f32_e32 v133, v156, v133
	v_pk_mul_f32 v[160:161], v[158:159], v[158:159]
	v_add_f32_e32 v133, v157, v133
	v_pk_add_f32 v[162:163], v[68:69], v[134:135] op_sel_hi:[1,0] neg_lo:[0,1] neg_hi:[0,1]
	v_add_f32_e32 v133, v160, v133
	v_pk_mul_f32 v[164:165], v[162:163], v[162:163]
	v_add_f32_e32 v133, v161, v133
	v_pk_add_f32 v[138:139], v[64:65], v[134:135] op_sel_hi:[1,0] neg_lo:[0,1] neg_hi:[0,1]
	v_pk_add_f32 v[142:143], v[66:67], v[134:135] op_sel_hi:[1,0] neg_lo:[0,1] neg_hi:[0,1]
	v_pk_add_f32 v[134:135], v[70:71], v[134:135] op_sel_hi:[1,0] neg_lo:[0,1] neg_hi:[0,1]
	v_add_f32_e32 v133, v164, v133
	v_pk_mul_f32 v[166:167], v[134:135], v[134:135]
	v_add_f32_e32 v133, v165, v133
	v_add_f32_e32 v133, v166, v133
	v_pk_mul_f32 v[140:141], v[138:139], v[138:139]
	v_add_f32_e32 v133, v167, v133
	v_add_f32_e32 v133, v140, v133
	v_pk_mul_f32 v[144:145], v[142:143], v[142:143]
	v_add_f32_e32 v133, v141, v133
	v_add_f32_e32 v133, v144, v133
	v_add_f32_e32 v133, v145, v133
	ds_bpermute_b32 v137, v137, v133
	v_lshlrev_b32_e32 v144, 1, v129
	v_mov_b32_e32 v145, v177
	s_waitcnt lgkmcnt(0)
	v_add_f32_e32 v133, v133, v137
	ds_bpermute_b32 v137, v168, v133
	v_add_u32_e32 v140, 0x1ff0, v130
	v_lshrrev_b32_e32 v140, 14, v140
	v_mul_u32_u24_e32 v141, 0x2010, v140
	v_sub_u32_e32 v141, v130, v141
	v_min_u32_e32 v141, 0x205f, v141
	v_mul_u32_u24_e32 v140, 0x101000, v140
	v_lshl_add_u32 v140, v141, 7, v140
	v_and_b32_e32 v141, 31, v141
	v_mul_u32_u24_e32 v141, 0x70, v141
	v_sub_u32_e32 v140, v140, v141
	v_and_b32_e32 v141, 16, v144
	v_lshl_add_u32 v140, v141, 5, v140
	v_and_b32_e32 v141, 8, v144
	v_add_u32_e32 v140, v140, v141
	v_mov_b32_e32 v141, 0
	v_lshl_add_u64 v[140:141], s[8:9], 0, v[140:141]
	s_waitcnt lgkmcnt(0)
	v_add_f32_e32 v133, v133, v137
	v_fmamk_f32 v133, v133, 0x3c800000, v196
	v_mul_f32_e32 v137, 0x4b800000, v133
	v_cmp_gt_f32_e32 vcc, s4, v133
	s_nop 1
	v_cndmask_b32_e32 v133, v133, v137, vcc
	v_rsq_f32_e32 v133, v133
	s_nop 0
	v_mul_f32_e32 v129, 0x45800000, v133
	v_cndmask_b32_e32 v144, v133, v129, vcc
	v_pk_mul_f32 v[146:147], v[146:147], v[144:145] op_sel_hi:[1,0]
	v_pk_mul_f32 v[148:149], v[150:151], v[144:145] op_sel_hi:[1,0]
	v_cvt_pk_f16_f32 v146, v146, v147
	v_cvt_pk_f16_f32 v147, v148, v149
	global_store_dwordx2 v[140:141], v[146:147], off
	v_pk_mul_f32 v[146:147], v[154:155], v[144:145] op_sel_hi:[1,0]
	v_pk_mul_f32 v[148:149], v[158:159], v[144:145] op_sel_hi:[1,0]
	v_cvt_pk_f16_f32 v146, v146, v147
	v_cvt_pk_f16_f32 v147, v148, v149
	global_store_dwordx2 v[140:141], v[146:147], off offset:1024
	v_pk_mul_f32 v[146:147], v[162:163], v[144:145] op_sel_hi:[1,0]
	v_pk_mul_f32 v[134:135], v[134:135], v[144:145] op_sel_hi:[1,0]
	v_cvt_pk_f16_f32 v146, v146, v147
	v_cvt_pk_f16_f32 v147, v134, v135
	v_pk_mov_b32 v[134:135], v[138:139], v[142:143] op_sel:[1,0]
	v_fma_mixlo_f16 v129, v138, v144, 0
	v_pk_mul_f32 v[134:135], v[134:135], v[144:145] op_sel_hi:[1,0]
	global_store_dwordx2 v[140:141], v[146:147], off offset:2048
	v_cvt_pk_f16_f32 v133, v134, v135
	v_pack_b32_f16 v134, v129, v133
	v_fma_mixlo_f16 v129, v143, v144, 0
	v_alignbit_b32 v135, v129, v133, 16
	global_store_dwordx2 v[140:141], v[134:135], off offset:3072

.LBB0_764:
	s_andn2_saveexec_b64 s[4:5], s[4:5]
	s_cbranch_execz .LBB0_766
	v_mov_b32_e32 v66, v61
	v_mov_b32_e32 v67, v62
	v_mov_b32_e32 v70, v60
	v_mov_b32_e32 v71, v63
	v_pk_add_f32 v[66:67], v[66:67], v[70:71]
	v_mov_b32_e32 v70, v57
	v_mov_b32_e32 v71, v58
	v_mov_b32_e32 v74, v56
	v_mov_b32_e32 v75, v59
	v_pk_add_f32 v[70:71], v[70:71], v[74:75]
	v_add_f32_e32 v66, v66, v67
	v_pk_add_f32 v[70:71], v[70:71], v[70:71] op_sel:[0,1] op_sel_hi:[1,0]
	v_add_f32_e32 v66, 0, v66
	v_add_f32_e32 v74, v52, v53
	v_add_f32_e32 v76, v54, v55
	v_mov_b32_e32 v67, v48
	v_mov_b32_e32 v71, v49
	v_mov_b32_e32 v75, v50
	v_mov_b32_e32 v77, v51
	v_pk_add_f32 v[66:67], v[66:67], v[70:71]
	v_pk_add_f32 v[70:71], v[74:75], v[76:77]
	v_cmp_lt_i32_e32 vcc, v203, v201
	v_pk_add_f32 v[66:67], v[66:67], v[70:71]
	s_mov_b32 s21, 0x800000
	v_add_f32_e32 v66, v66, v67
	v_cndmask_b32_e32 v67, v199, v203, vcc
	v_lshlrev_b32_e32 v73, 2, v67
	ds_bpermute_b32 v67, v73, v66
	v_cmp_lt_i32_e32 vcc, v202, v201
	v_lshlrev_b32_e32 v176, 1, v65
	s_waitcnt lgkmcnt(0)
	v_add_f32_e32 v66, v66, v67
	v_cndmask_b32_e32 v67, v199, v202, vcc
	v_lshlrev_b32_e32 v102, 2, v67
	ds_bpermute_b32 v67, v102, v66
	s_waitcnt lgkmcnt(0)
	v_add_f32_e32 v66, v66, v67
	v_mul_f32_e32 v66, 0x3c800000, v66
	v_pk_add_f32 v[80:81], v[60:61], v[66:67] op_sel_hi:[1,0] neg_lo:[0,1] neg_hi:[0,1]
	v_pk_add_f32 v[84:85], v[62:63], v[66:67] op_sel_hi:[1,0] neg_lo:[0,1] neg_hi:[0,1]
	v_pk_mul_f32 v[82:83], v[80:81], v[80:81]
	v_pk_mul_f32 v[86:87], v[84:85], v[84:85]
	v_add_f32_e32 v82, v82, v83
	v_pk_add_f32 v[88:89], v[56:57], v[66:67] op_sel_hi:[1,0] neg_lo:[0,1] neg_hi:[0,1]
	v_add_f32_e32 v82, v86, v82
	v_pk_mul_f32 v[90:91], v[88:89], v[88:89]
	v_add_f32_e32 v82, v87, v82
	v_pk_add_f32 v[92:93], v[58:59], v[66:67] op_sel_hi:[1,0] neg_lo:[0,1] neg_hi:[0,1]
	v_add_f32_e32 v82, v90, v82
	v_pk_mul_f32 v[94:95], v[92:93], v[92:93]
	v_add_f32_e32 v82, v91, v82
	v_pk_add_f32 v[96:97], v[52:53], v[66:67] op_sel_hi:[1,0] neg_lo:[0,1] neg_hi:[0,1]
	v_add_f32_e32 v82, v94, v82
	v_pk_mul_f32 v[98:99], v[96:97], v[96:97]
	v_add_f32_e32 v82, v95, v82
	v_pk_add_f32 v[70:71], v[48:49], v[66:67] op_sel_hi:[1,0] neg_lo:[0,1] neg_hi:[0,1]
	v_pk_add_f32 v[76:77], v[50:51], v[66:67] op_sel_hi:[1,0] neg_lo:[0,1] neg_hi:[0,1]
	v_pk_add_f32 v[66:67], v[54:55], v[66:67] op_sel_hi:[1,0] neg_lo:[0,1] neg_hi:[0,1]
	v_add_f32_e32 v82, v98, v82
	v_pk_mul_f32 v[100:101], v[66:67], v[66:67]
	v_add_f32_e32 v82, v99, v82
	v_add_f32_e32 v82, v100, v82
	v_pk_mul_f32 v[74:75], v[70:71], v[70:71]
	v_add_f32_e32 v82, v101, v82
	v_add_f32_e32 v74, v74, v82
	v_pk_mul_f32 v[78:79], v[76:77], v[76:77]
	v_add_f32_e32 v74, v75, v74
	v_add_f32_e32 v74, v78, v74
	v_add_f32_e32 v74, v79, v74
	ds_bpermute_b32 v73, v73, v74
	s_waitcnt lgkmcnt(0)
	v_add_f32_e32 v73, v74, v73
	ds_bpermute_b32 v78, v102, v73
	v_add_u32_e32 v74, 0x1ff0, v68
	v_lshrrev_b32_e32 v74, 14, v74
	v_mul_u32_u24_e32 v75, 0x2010, v74
	v_sub_u32_e32 v75, v68, v75
	v_min_u32_e32 v75, 0x205f, v75
	v_mul_u32_u24_e32 v74, 0x101000, v74
	v_lshl_add_u32 v74, v75, 7, v74
	v_and_b32_e32 v75, 31, v75
	v_mul_u32_u24_e32 v75, 0x70, v75
	v_sub_u32_e32 v74, v74, v75
	v_and_b32_e32 v75, 16, v176
	v_lshl_add_u32 v74, v75, 5, v74
	v_and_b32_e32 v75, 8, v176
	v_add_u32_e32 v74, v74, v75
	v_mov_b32_e32 v75, 0
	v_lshl_add_u64 v[74:75], s[8:9], 0, v[74:75]
	s_waitcnt lgkmcnt(0)
	v_add_f32_e32 v73, v73, v78
	v_fmamk_f32 v73, v73, 0x3c800000, v196
	v_mul_f32_e32 v78, 0x4b800000, v73
	v_cmp_gt_f32_e32 vcc, s21, v73
	s_nop 1
	v_cndmask_b32_e32 v73, v73, v78, vcc
	v_rsq_f32_e32 v73, v73
	s_nop 0
	v_mul_f32_e32 v78, 0x45800000, v73
	v_cndmask_b32_e32 v78, v73, v78, vcc
	v_pk_mul_f32 v[80:81], v[80:81], v[78:79] op_sel_hi:[1,0]
	v_pk_mul_f32 v[82:83], v[84:85], v[78:79] op_sel_hi:[1,0]
	v_cvt_pk_f16_f32 v80, v80, v81
	v_cvt_pk_f16_f32 v81, v82, v83
	global_store_dwordx2 v[74:75], v[80:81], off
	v_pk_mul_f32 v[80:81], v[88:89], v[78:79] op_sel_hi:[1,0]
	v_pk_mul_f32 v[82:83], v[92:93], v[78:79] op_sel_hi:[1,0]
	v_cvt_pk_f16_f32 v80, v80, v81
	v_cvt_pk_f16_f32 v81, v82, v83
	global_store_dwordx2 v[74:75], v[80:81], off offset:1024
	v_pk_mul_f32 v[80:81], v[96:97], v[78:79] op_sel_hi:[1,0]
	v_pk_mul_f32 v[66:67], v[66:67], v[78:79] op_sel_hi:[1,0]
	v_cvt_pk_f16_f32 v80, v80, v81
	v_cvt_pk_f16_f32 v81, v66, v67
	v_pk_mov_b32 v[66:67], v[70:71], v[76:77] op_sel:[1,0]
	v_fma_mixlo_f16 v73, v70, v78, 0
	v_pk_mul_f32 v[66:67], v[66:67], v[78:79] op_sel_hi:[1,0]
	v_fma_mixlo_f16 v70, v77, v78, 0
	v_cvt_pk_f16_f32 v67, v66, v67
	v_pack_b32_f16 v66, v73, v67
	v_alignbit_b32 v67, v70, v67, 16
	global_store_dwordx2 v[74:75], v[80:81], off offset:2048
	global_store_dwordx2 v[74:75], v[66:67], off offset:3072

.LBB0_776:
	s_andn2_saveexec_b64 s[24:25], s[24:25]
	s_cbranch_execz .LBB0_778
	v_mov_b32_e32 v74, v45
	v_mov_b32_e32 v75, v46
	v_mov_b32_e32 v76, v44
	v_mov_b32_e32 v77, v47
	v_pk_add_f32 v[74:75], v[74:75], v[76:77]
	v_mov_b32_e32 v76, v41
	v_mov_b32_e32 v77, v42
	v_mov_b32_e32 v78, v40
	v_mov_b32_e32 v79, v43
	v_pk_add_f32 v[76:77], v[76:77], v[78:79]
	v_add_f32_e32 v67, v74, v75
	v_pk_add_f32 v[76:77], v[76:77], v[76:77] op_sel:[0,1] op_sel_hi:[1,0]
	v_add_f32_e32 v74, 0, v67
	v_add_f32_e32 v78, v36, v37
	v_add_f32_e32 v80, v38, v39
	v_mov_b32_e32 v75, v32
	v_mov_b32_e32 v77, v33
	v_mov_b32_e32 v79, v34
	v_mov_b32_e32 v81, v35
	v_pk_add_f32 v[74:75], v[74:75], v[76:77]
	v_pk_add_f32 v[76:77], v[78:79], v[80:81]
	v_cmp_lt_i32_e32 vcc, v203, v201
	v_pk_add_f32 v[74:75], v[74:75], v[76:77]
	s_mov_b32 s21, 0x800000
	v_cndmask_b32_e32 v69, v199, v203, vcc
	v_add_f32_e32 v67, v74, v75
	v_lshlrev_b32_e32 v69, 2, v69
	ds_bpermute_b32 v73, v69, v67
	v_cmp_lt_i32_e32 vcc, v202, v201
	s_waitcnt lgkmcnt(0)
	v_add_f32_e32 v67, v67, v73
	v_cndmask_b32_e32 v73, v199, v202, vcc
	v_lshlrev_b32_e32 v73, 2, v73
	ds_bpermute_b32 v74, v73, v67
	s_waitcnt lgkmcnt(0)
	v_add_f32_e32 v67, v67, v74
	v_mul_f32_e32 v74, 0x3c800000, v67
	v_pk_add_f32 v[84:85], v[44:45], v[74:75] op_sel_hi:[1,0] neg_lo:[0,1] neg_hi:[0,1]
	v_pk_add_f32 v[88:89], v[46:47], v[74:75] op_sel_hi:[1,0] neg_lo:[0,1] neg_hi:[0,1]
	v_pk_mul_f32 v[86:87], v[84:85], v[84:85]
	v_pk_mul_f32 v[90:91], v[88:89], v[88:89]
	v_add_f32_e32 v67, v86, v87
	v_pk_add_f32 v[92:93], v[40:41], v[74:75] op_sel_hi:[1,0] neg_lo:[0,1] neg_hi:[0,1]
	v_add_f32_e32 v67, v90, v67
	v_pk_mul_f32 v[94:95], v[92:93], v[92:93]
	v_add_f32_e32 v67, v91, v67
	v_pk_add_f32 v[96:97], v[42:43], v[74:75] op_sel_hi:[1,0] neg_lo:[0,1] neg_hi:[0,1]
	v_add_f32_e32 v67, v94, v67
	v_pk_mul_f32 v[98:99], v[96:97], v[96:97]
	v_add_f32_e32 v67, v95, v67
	v_pk_add_f32 v[100:101], v[36:37], v[74:75] op_sel_hi:[1,0] neg_lo:[0,1] neg_hi:[0,1]
	v_add_f32_e32 v67, v98, v67
	v_pk_mul_f32 v[102:103], v[100:101], v[100:101]
	v_add_f32_e32 v67, v99, v67
	v_pk_add_f32 v[76:77], v[32:33], v[74:75] op_sel_hi:[1,0] neg_lo:[0,1] neg_hi:[0,1]
	v_pk_add_f32 v[80:81], v[34:35], v[74:75] op_sel_hi:[1,0] neg_lo:[0,1] neg_hi:[0,1]
	v_pk_add_f32 v[74:75], v[38:39], v[74:75] op_sel_hi:[1,0] neg_lo:[0,1] neg_hi:[0,1]
	v_add_f32_e32 v67, v102, v67
	v_pk_mul_f32 v[104:105], v[74:75], v[74:75]
	v_add_f32_e32 v67, v103, v67
	v_add_f32_e32 v67, v104, v67
	v_pk_mul_f32 v[78:79], v[76:77], v[76:77]
	v_add_f32_e32 v67, v105, v67
	v_add_f32_e32 v67, v78, v67
	v_pk_mul_f32 v[82:83], v[80:81], v[80:81]
	v_add_f32_e32 v67, v79, v67
	v_add_f32_e32 v67, v82, v67
	v_add_f32_e32 v67, v83, v67
	ds_bpermute_b32 v69, v69, v67
	v_lshlrev_b32_e32 v82, 1, v65
	v_mov_b32_e32 v83, v177
	s_waitcnt lgkmcnt(0)
	v_add_f32_e32 v67, v67, v69
	ds_bpermute_b32 v69, v73, v67
	v_add_u32_e32 v78, 0x1ff0, v70
	v_lshrrev_b32_e32 v78, 14, v78
	v_mul_u32_u24_e32 v79, 0x2010, v78
	v_sub_u32_e32 v79, v70, v79
	v_min_u32_e32 v79, 0x205f, v79
	v_mul_u32_u24_e32 v78, 0x101000, v78
	v_lshl_add_u32 v78, v79, 7, v78
	v_and_b32_e32 v79, 31, v79
	v_mul_u32_u24_e32 v79, 0x70, v79
	v_sub_u32_e32 v78, v78, v79
	v_and_b32_e32 v79, 16, v82
	v_lshl_add_u32 v78, v79, 5, v78
	v_and_b32_e32 v79, 8, v82
	v_add_u32_e32 v78, v78, v79
	v_mov_b32_e32 v79, 0
	v_lshl_add_u64 v[78:79], s[8:9], 0, v[78:79]
	s_waitcnt lgkmcnt(0)
	v_add_f32_e32 v67, v67, v69
	v_fmamk_f32 v67, v67, 0x3c800000, v196
	v_mul_f32_e32 v69, 0x4b800000, v67
	v_cmp_gt_f32_e32 vcc, s21, v67
	s_nop 1
	v_cndmask_b32_e32 v67, v67, v69, vcc
	v_rsq_f32_e32 v67, v67
	s_nop 0
	v_mul_f32_e32 v69, 0x45800000, v67
	v_cndmask_b32_e32 v82, v67, v69, vcc
	v_pk_mul_f32 v[84:85], v[84:85], v[82:83] op_sel_hi:[1,0]
	v_pk_mul_f32 v[86:87], v[88:89], v[82:83] op_sel_hi:[1,0]
	v_cvt_pk_f16_f32 v84, v84, v85
	v_cvt_pk_f16_f32 v85, v86, v87
	global_store_dwordx2 v[78:79], v[84:85], off
	v_pk_mul_f32 v[84:85], v[92:93], v[82:83] op_sel_hi:[1,0]
	v_pk_mul_f32 v[86:87], v[96:97], v[82:83] op_sel_hi:[1,0]
	v_cvt_pk_f16_f32 v84, v84, v85
	v_cvt_pk_f16_f32 v85, v86, v87
	global_store_dwordx2 v[78:79], v[84:85], off offset:1024
	v_pk_mul_f32 v[84:85], v[100:101], v[82:83] op_sel_hi:[1,0]
	v_pk_mul_f32 v[74:75], v[74:75], v[82:83] op_sel_hi:[1,0]
	v_cvt_pk_f16_f32 v84, v84, v85
	v_cvt_pk_f16_f32 v85, v74, v75
	v_pk_mov_b32 v[74:75], v[76:77], v[80:81] op_sel:[1,0]
	v_fma_mixlo_f16 v67, v76, v82, 0
	v_pk_mul_f32 v[74:75], v[74:75], v[82:83] op_sel_hi:[1,0]
	global_store_dwordx2 v[78:79], v[84:85], off offset:2048
	v_cvt_pk_f16_f32 v69, v74, v75
	v_pack_b32_f16 v74, v67, v69
	v_fma_mixlo_f16 v67, v81, v82, 0
	v_alignbit_b32 v75, v67, v69, 16
	global_store_dwordx2 v[78:79], v[74:75], off offset:3072

.LBB0_788:
	s_andn2_saveexec_b64 s[24:25], s[24:25]
	s_cbranch_execz .LBB0_790
	v_mov_b32_e32 v74, v29
	v_mov_b32_e32 v75, v30
	v_mov_b32_e32 v76, v28
	v_mov_b32_e32 v77, v31
	v_pk_add_f32 v[74:75], v[74:75], v[76:77]
	v_mov_b32_e32 v76, v25
	v_mov_b32_e32 v77, v26
	v_mov_b32_e32 v78, v24
	v_mov_b32_e32 v79, v27
	v_pk_add_f32 v[76:77], v[76:77], v[78:79]
	v_add_f32_e32 v67, v74, v75
	v_pk_add_f32 v[76:77], v[76:77], v[76:77] op_sel:[0,1] op_sel_hi:[1,0]
	v_add_f32_e32 v74, 0, v67
	v_add_f32_e32 v78, v20, v21
	v_add_f32_e32 v80, v22, v23
	v_mov_b32_e32 v75, v16
	v_mov_b32_e32 v77, v17
	v_mov_b32_e32 v79, v18
	v_mov_b32_e32 v81, v19
	v_pk_add_f32 v[74:75], v[74:75], v[76:77]
	v_pk_add_f32 v[76:77], v[78:79], v[80:81]
	v_cmp_lt_i32_e32 vcc, v203, v201
	v_pk_add_f32 v[74:75], v[74:75], v[76:77]
	s_mov_b32 s21, 0x800000
	v_cndmask_b32_e32 v69, v199, v203, vcc
	v_add_f32_e32 v67, v74, v75
	v_lshlrev_b32_e32 v69, 2, v69
	ds_bpermute_b32 v73, v69, v67
	v_cmp_lt_i32_e32 vcc, v202, v201
	s_waitcnt lgkmcnt(0)
	v_add_f32_e32 v67, v67, v73
	v_cndmask_b32_e32 v73, v199, v202, vcc
	v_lshlrev_b32_e32 v73, 2, v73
	ds_bpermute_b32 v74, v73, v67
	s_waitcnt lgkmcnt(0)
	v_add_f32_e32 v67, v67, v74
	v_mul_f32_e32 v74, 0x3c800000, v67
	v_pk_add_f32 v[84:85], v[28:29], v[74:75] op_sel_hi:[1,0] neg_lo:[0,1] neg_hi:[0,1]
	v_pk_add_f32 v[88:89], v[30:31], v[74:75] op_sel_hi:[1,0] neg_lo:[0,1] neg_hi:[0,1]
	v_pk_mul_f32 v[86:87], v[84:85], v[84:85]
	v_pk_mul_f32 v[90:91], v[88:89], v[88:89]
	v_add_f32_e32 v67, v86, v87
	v_pk_add_f32 v[92:93], v[24:25], v[74:75] op_sel_hi:[1,0] neg_lo:[0,1] neg_hi:[0,1]
	v_add_f32_e32 v67, v90, v67
	v_pk_mul_f32 v[94:95], v[92:93], v[92:93]
	v_add_f32_e32 v67, v91, v67
	v_pk_add_f32 v[96:97], v[26:27], v[74:75] op_sel_hi:[1,0] neg_lo:[0,1] neg_hi:[0,1]
	v_add_f32_e32 v67, v94, v67
	v_pk_mul_f32 v[98:99], v[96:97], v[96:97]
	v_add_f32_e32 v67, v95, v67
	v_pk_add_f32 v[100:101], v[20:21], v[74:75] op_sel_hi:[1,0] neg_lo:[0,1] neg_hi:[0,1]
	v_add_f32_e32 v67, v98, v67
	v_pk_mul_f32 v[102:103], v[100:101], v[100:101]
	v_add_f32_e32 v67, v99, v67
	v_pk_add_f32 v[76:77], v[16:17], v[74:75] op_sel_hi:[1,0] neg_lo:[0,1] neg_hi:[0,1]
	v_pk_add_f32 v[80:81], v[18:19], v[74:75] op_sel_hi:[1,0] neg_lo:[0,1] neg_hi:[0,1]
	v_pk_add_f32 v[74:75], v[22:23], v[74:75] op_sel_hi:[1,0] neg_lo:[0,1] neg_hi:[0,1]
	v_add_f32_e32 v67, v102, v67
	v_pk_mul_f32 v[104:105], v[74:75], v[74:75]
	v_add_f32_e32 v67, v103, v67
	v_add_f32_e32 v67, v104, v67
	v_pk_mul_f32 v[78:79], v[76:77], v[76:77]
	v_add_f32_e32 v67, v105, v67
	v_add_f32_e32 v67, v78, v67
	v_pk_mul_f32 v[82:83], v[80:81], v[80:81]
	v_add_f32_e32 v67, v79, v67
	v_add_f32_e32 v67, v82, v67
	v_add_f32_e32 v67, v83, v67
	ds_bpermute_b32 v69, v69, v67
	v_lshlrev_b32_e32 v82, 1, v65
	v_mov_b32_e32 v83, v177
	s_waitcnt lgkmcnt(0)
	v_add_f32_e32 v67, v67, v69
	ds_bpermute_b32 v69, v73, v67
	v_add_u32_e32 v78, 0x1ff0, v70
	v_lshrrev_b32_e32 v78, 14, v78
	v_mul_u32_u24_e32 v79, 0x2010, v78
	v_sub_u32_e32 v79, v70, v79
	v_min_u32_e32 v79, 0x205f, v79
	v_mul_u32_u24_e32 v78, 0x101000, v78
	v_lshl_add_u32 v78, v79, 7, v78
	v_and_b32_e32 v79, 31, v79
	v_mul_u32_u24_e32 v79, 0x70, v79
	v_sub_u32_e32 v78, v78, v79
	v_and_b32_e32 v79, 16, v82
	v_lshl_add_u32 v78, v79, 5, v78
	v_and_b32_e32 v79, 8, v82
	v_add_u32_e32 v78, v78, v79
	v_mov_b32_e32 v79, 0
	v_lshl_add_u64 v[78:79], s[8:9], 0, v[78:79]
	s_waitcnt lgkmcnt(0)
	v_add_f32_e32 v67, v67, v69
	v_fmamk_f32 v67, v67, 0x3c800000, v196
	v_mul_f32_e32 v69, 0x4b800000, v67
	v_cmp_gt_f32_e32 vcc, s21, v67
	s_nop 1
	v_cndmask_b32_e32 v67, v67, v69, vcc
	v_rsq_f32_e32 v67, v67
	s_nop 0
	v_mul_f32_e32 v69, 0x45800000, v67
	v_cndmask_b32_e32 v82, v67, v69, vcc
	v_pk_mul_f32 v[84:85], v[84:85], v[82:83] op_sel_hi:[1,0]
	v_pk_mul_f32 v[86:87], v[88:89], v[82:83] op_sel_hi:[1,0]
	v_cvt_pk_f16_f32 v84, v84, v85
	v_cvt_pk_f16_f32 v85, v86, v87
	global_store_dwordx2 v[78:79], v[84:85], off
	v_pk_mul_f32 v[84:85], v[92:93], v[82:83] op_sel_hi:[1,0]
	v_pk_mul_f32 v[86:87], v[96:97], v[82:83] op_sel_hi:[1,0]
	v_cvt_pk_f16_f32 v84, v84, v85
	v_cvt_pk_f16_f32 v85, v86, v87
	global_store_dwordx2 v[78:79], v[84:85], off offset:1024
	v_pk_mul_f32 v[84:85], v[100:101], v[82:83] op_sel_hi:[1,0]
	v_pk_mul_f32 v[74:75], v[74:75], v[82:83] op_sel_hi:[1,0]
	v_cvt_pk_f16_f32 v84, v84, v85
	v_cvt_pk_f16_f32 v85, v74, v75
	v_pk_mov_b32 v[74:75], v[76:77], v[80:81] op_sel:[1,0]
	v_fma_mixlo_f16 v67, v76, v82, 0
	v_pk_mul_f32 v[74:75], v[74:75], v[82:83] op_sel_hi:[1,0]
	global_store_dwordx2 v[78:79], v[84:85], off offset:2048
	v_cvt_pk_f16_f32 v69, v74, v75
	v_pack_b32_f16 v74, v67, v69
	v_fma_mixlo_f16 v67, v81, v82, 0
	v_alignbit_b32 v75, v67, v69, 16
	global_store_dwordx2 v[78:79], v[74:75], off offset:3072

.LBB0_800:
	s_andn2_saveexec_b64 s[0:1], s[0:1]
	s_cbranch_execz .LBB0_802
	v_mov_b32_e32 v70, v13
	v_mov_b32_e32 v71, v14
	v_mov_b32_e32 v74, v12
	v_mov_b32_e32 v75, v15
	v_pk_add_f32 v[70:71], v[70:71], v[74:75]
	v_mov_b32_e32 v74, v5
	v_mov_b32_e32 v75, v6
	v_mov_b32_e32 v76, v4
	v_mov_b32_e32 v77, v7
	v_pk_add_f32 v[74:75], v[74:75], v[76:77]
	v_add_f32_e32 v67, v70, v71
	v_pk_add_f32 v[74:75], v[74:75], v[74:75] op_sel:[0,1] op_sel_hi:[1,0]
	v_add_f32_e32 v70, 0, v67
	v_add_f32_e32 v76, v0, v1
	v_add_f32_e32 v78, v2, v3
	v_mov_b32_e32 v71, v8
	v_mov_b32_e32 v75, v9
	v_mov_b32_e32 v77, v10
	v_mov_b32_e32 v79, v11
	v_pk_add_f32 v[70:71], v[70:71], v[74:75]
	v_pk_add_f32 v[74:75], v[76:77], v[78:79]
	v_cmp_lt_i32_e32 vcc, v203, v201
	v_pk_add_f32 v[70:71], v[70:71], v[74:75]
	s_mov_b32 s4, 0x800000
	v_add_f32_e32 v67, v70, v71
	v_cndmask_b32_e32 v70, v199, v203, vcc
	v_lshlrev_b32_e32 v73, 2, v70
	ds_bpermute_b32 v70, v73, v67
	v_cmp_lt_i32_e32 vcc, v202, v201
	s_waitcnt lgkmcnt(0)
	v_add_f32_e32 v67, v67, v70
	v_cndmask_b32_e32 v70, v199, v202, vcc
	v_lshlrev_b32_e32 v104, 2, v70
	ds_bpermute_b32 v70, v104, v67
	s_waitcnt lgkmcnt(0)
	v_add_f32_e32 v67, v67, v70
	v_mul_f32_e32 v70, 0x3c800000, v67
	v_pk_add_f32 v[82:83], v[12:13], v[70:71] op_sel_hi:[1,0] neg_lo:[0,1] neg_hi:[0,1]
	v_pk_add_f32 v[86:87], v[14:15], v[70:71] op_sel_hi:[1,0] neg_lo:[0,1] neg_hi:[0,1]
	v_pk_mul_f32 v[84:85], v[82:83], v[82:83]
	v_pk_mul_f32 v[88:89], v[86:87], v[86:87]
	v_add_f32_e32 v67, v84, v85
	v_pk_add_f32 v[90:91], v[4:5], v[70:71] op_sel_hi:[1,0] neg_lo:[0,1] neg_hi:[0,1]
	v_add_f32_e32 v67, v88, v67
	v_pk_mul_f32 v[92:93], v[90:91], v[90:91]
	v_add_f32_e32 v67, v89, v67
	v_pk_add_f32 v[94:95], v[6:7], v[70:71] op_sel_hi:[1,0] neg_lo:[0,1] neg_hi:[0,1]
	v_add_f32_e32 v67, v92, v67
	v_pk_mul_f32 v[96:97], v[94:95], v[94:95]
	v_add_f32_e32 v67, v93, v67
	v_pk_add_f32 v[98:99], v[0:1], v[70:71] op_sel_hi:[1,0] neg_lo:[0,1] neg_hi:[0,1]
	v_add_f32_e32 v67, v96, v67
	v_pk_mul_f32 v[100:101], v[98:99], v[98:99]
	v_add_f32_e32 v67, v97, v67
	v_pk_add_f32 v[74:75], v[8:9], v[70:71] op_sel_hi:[1,0] neg_lo:[0,1] neg_hi:[0,1]
	v_pk_add_f32 v[78:79], v[10:11], v[70:71] op_sel_hi:[1,0] neg_lo:[0,1] neg_hi:[0,1]
	v_pk_add_f32 v[70:71], v[2:3], v[70:71] op_sel_hi:[1,0] neg_lo:[0,1] neg_hi:[0,1]
	v_add_f32_e32 v67, v100, v67
	v_pk_mul_f32 v[102:103], v[70:71], v[70:71]
	v_add_f32_e32 v67, v101, v67
	v_add_f32_e32 v67, v102, v67
	v_pk_mul_f32 v[76:77], v[74:75], v[74:75]
	v_add_f32_e32 v67, v103, v67
	v_add_f32_e32 v67, v76, v67
	v_pk_mul_f32 v[80:81], v[78:79], v[78:79]
	v_add_f32_e32 v67, v77, v67
	v_add_f32_e32 v67, v80, v67
	v_add_f32_e32 v67, v81, v67
	ds_bpermute_b32 v73, v73, v67
	v_lshlrev_b32_e32 v80, 1, v65
	v_mov_b32_e32 v81, v177
	s_waitcnt lgkmcnt(0)
	v_add_f32_e32 v67, v67, v73
	ds_bpermute_b32 v73, v104, v67
	v_add_u32_e32 v76, 0x1ff0, v68
	v_lshrrev_b32_e32 v76, 14, v76
	v_mul_u32_u24_e32 v77, 0x2010, v76
	v_sub_u32_e32 v77, v68, v77
	v_min_u32_e32 v77, 0x205f, v77
	v_mul_u32_u24_e32 v76, 0x101000, v76
	v_lshl_add_u32 v76, v77, 7, v76
	v_and_b32_e32 v77, 31, v77
	v_mul_u32_u24_e32 v77, 0x70, v77
	v_sub_u32_e32 v76, v76, v77
	v_and_b32_e32 v77, 16, v80
	v_lshl_add_u32 v76, v77, 5, v76
	v_and_b32_e32 v77, 8, v80
	v_add_u32_e32 v76, v76, v77
	v_mov_b32_e32 v77, 0
	v_lshl_add_u64 v[76:77], s[8:9], 0, v[76:77]
	s_waitcnt lgkmcnt(0)
	v_add_f32_e32 v67, v67, v73
	v_fmamk_f32 v67, v67, 0x3c800000, v196
	v_mul_f32_e32 v73, 0x4b800000, v67
	v_cmp_gt_f32_e32 vcc, s4, v67
	s_nop 1
	v_cndmask_b32_e32 v67, v67, v73, vcc
	v_rsq_f32_e32 v67, v67
	s_nop 0
	v_mul_f32_e32 v65, 0x45800000, v67
	v_cndmask_b32_e32 v80, v67, v65, vcc
	v_pk_mul_f32 v[82:83], v[82:83], v[80:81] op_sel_hi:[1,0]
	v_pk_mul_f32 v[84:85], v[86:87], v[80:81] op_sel_hi:[1,0]
	v_cvt_pk_f16_f32 v82, v82, v83
	v_cvt_pk_f16_f32 v83, v84, v85
	global_store_dwordx2 v[76:77], v[82:83], off
	v_pk_mul_f32 v[82:83], v[90:91], v[80:81] op_sel_hi:[1,0]
	v_pk_mul_f32 v[84:85], v[94:95], v[80:81] op_sel_hi:[1,0]
	v_cvt_pk_f16_f32 v82, v82, v83
	v_cvt_pk_f16_f32 v83, v84, v85
	global_store_dwordx2 v[76:77], v[82:83], off offset:1024
	v_pk_mul_f32 v[82:83], v[98:99], v[80:81] op_sel_hi:[1,0]
	v_pk_mul_f32 v[70:71], v[70:71], v[80:81] op_sel_hi:[1,0]
	v_cvt_pk_f16_f32 v82, v82, v83
	v_cvt_pk_f16_f32 v83, v70, v71
	v_pk_mov_b32 v[70:71], v[74:75], v[78:79] op_sel:[1,0]
	v_fma_mixlo_f16 v65, v74, v80, 0
	v_pk_mul_f32 v[70:71], v[70:71], v[80:81] op_sel_hi:[1,0]
	global_store_dwordx2 v[76:77], v[82:83], off offset:2048
	v_cvt_pk_f16_f32 v67, v70, v71
	v_pack_b32_f16 v70, v65, v67
	v_fma_mixlo_f16 v65, v79, v80, 0
	v_alignbit_b32 v71, v65, v67, 16
	global_store_dwordx2 v[76:77], v[70:71], off offset:3072

.LBB0_890:
	s_andn2_saveexec_b64 s[4:5], s[4:5]
	s_cbranch_execz .LBB0_892
	v_mov_b32_e32 v64, v61
	v_mov_b32_e32 v65, v62
	v_mov_b32_e32 v68, v60
	v_mov_b32_e32 v69, v63
	v_pk_add_f32 v[64:65], v[64:65], v[68:69]
	v_mov_b32_e32 v68, v57
	v_mov_b32_e32 v69, v58
	s_waitcnt vmcnt(13)
	v_mov_b32_e32 v72, v56
	v_mov_b32_e32 v73, v59
	v_pk_add_f32 v[68:69], v[68:69], v[72:73]
	v_add_f32_e32 v64, v64, v65
	v_pk_add_f32 v[68:69], v[68:69], v[68:69] op_sel:[0,1] op_sel_hi:[1,0]
	v_add_f32_e32 v64, 0, v64
	v_add_f32_e32 v72, v52, v53
	v_add_f32_e32 v74, v54, v55
	v_mov_b32_e32 v65, v48
	v_mov_b32_e32 v69, v49
	v_mov_b32_e32 v73, v50
	v_mov_b32_e32 v75, v51
	v_pk_add_f32 v[64:65], v[64:65], v[68:69]
	v_pk_add_f32 v[68:69], v[72:73], v[74:75]
	v_cmp_lt_i32_e32 vcc, v203, v201
	v_pk_add_f32 v[64:65], v[64:65], v[68:69]
	s_mov_b32 s17, 0x800000
	v_add_f32_e32 v64, v64, v65
	v_cndmask_b32_e32 v65, v199, v203, vcc
	s_waitcnt vmcnt(6)
	v_lshlrev_b32_e32 v100, 2, v65
	ds_bpermute_b32 v65, v100, v64
	v_cmp_lt_i32_e32 vcc, v202, v201
	v_lshlrev_b32_e32 v176, 1, v71
	s_waitcnt lgkmcnt(0)
	v_add_f32_e32 v64, v64, v65
	v_cndmask_b32_e32 v65, v199, v202, vcc
	v_lshlrev_b32_e32 v101, 2, v65
	ds_bpermute_b32 v65, v101, v64
	s_waitcnt lgkmcnt(0)
	v_add_f32_e32 v64, v64, v65
	v_mul_f32_e32 v64, 0x3c800000, v64
	v_pk_add_f32 v[78:79], v[60:61], v[64:65] op_sel_hi:[1,0] neg_lo:[0,1] neg_hi:[0,1]
	v_pk_add_f32 v[82:83], v[62:63], v[64:65] op_sel_hi:[1,0] neg_lo:[0,1] neg_hi:[0,1]
	v_pk_mul_f32 v[80:81], v[78:79], v[78:79]
	v_pk_mul_f32 v[84:85], v[82:83], v[82:83]
	v_add_f32_e32 v80, v80, v81
	v_pk_add_f32 v[86:87], v[56:57], v[64:65] op_sel_hi:[1,0] neg_lo:[0,1] neg_hi:[0,1]
	v_add_f32_e32 v80, v84, v80
	v_pk_mul_f32 v[88:89], v[86:87], v[86:87]
	v_add_f32_e32 v80, v85, v80
	v_pk_add_f32 v[90:91], v[58:59], v[64:65] op_sel_hi:[1,0] neg_lo:[0,1] neg_hi:[0,1]
	v_add_f32_e32 v80, v88, v80
	v_pk_mul_f32 v[92:93], v[90:91], v[90:91]
	v_add_f32_e32 v80, v89, v80
	v_pk_add_f32 v[94:95], v[52:53], v[64:65] op_sel_hi:[1,0] neg_lo:[0,1] neg_hi:[0,1]
	v_add_f32_e32 v80, v92, v80
	v_pk_mul_f32 v[96:97], v[94:95], v[94:95]
	v_add_f32_e32 v80, v93, v80
	v_pk_add_f32 v[68:69], v[48:49], v[64:65] op_sel_hi:[1,0] neg_lo:[0,1] neg_hi:[0,1]
	v_pk_add_f32 v[74:75], v[50:51], v[64:65] op_sel_hi:[1,0] neg_lo:[0,1] neg_hi:[0,1]
	v_pk_add_f32 v[64:65], v[54:55], v[64:65] op_sel_hi:[1,0] neg_lo:[0,1] neg_hi:[0,1]
	v_add_f32_e32 v80, v96, v80
	v_pk_mul_f32 v[98:99], v[64:65], v[64:65]
	v_add_f32_e32 v80, v97, v80
	v_add_f32_e32 v80, v98, v80
	v_pk_mul_f32 v[72:73], v[68:69], v[68:69]
	v_add_f32_e32 v80, v99, v80
	v_add_f32_e32 v72, v72, v80
	v_pk_mul_f32 v[76:77], v[74:75], v[74:75]
	v_add_f32_e32 v72, v73, v72
	v_add_f32_e32 v72, v76, v72
	v_add_f32_e32 v72, v77, v72
	ds_bpermute_b32 v73, v100, v72
	s_waitcnt lgkmcnt(0)
	v_add_f32_e32 v76, v72, v73
	ds_bpermute_b32 v77, v101, v76
	v_add_u32_e32 v72, 0x1ff0, v66
	v_lshrrev_b32_e32 v72, 14, v72
	v_mul_u32_u24_e32 v73, 0x2010, v72
	v_sub_u32_e32 v73, v66, v73
	v_min_u32_e32 v73, 0x205f, v73
	v_mul_u32_u24_e32 v72, 0x101000, v72
	v_lshl_add_u32 v72, v73, 7, v72
	v_and_b32_e32 v73, 31, v73
	v_mul_u32_u24_e32 v73, 0x70, v73
	v_sub_u32_e32 v72, v72, v73
	v_and_b32_e32 v73, 16, v176
	v_lshl_add_u32 v72, v73, 5, v72
	v_and_b32_e32 v73, 8, v176
	v_add_u32_e32 v72, v72, v73
	v_mov_b32_e32 v73, 0
	v_lshl_add_u64 v[72:73], s[8:9], 0, v[72:73]
	s_waitcnt lgkmcnt(0)
	v_add_f32_e32 v76, v76, v77
	v_fmamk_f32 v76, v76, 0x3c800000, v196
	v_mul_f32_e32 v77, 0x4b800000, v76
	v_cmp_gt_f32_e32 vcc, s17, v76
	s_nop 1
	v_cndmask_b32_e32 v76, v76, v77, vcc
	v_rsq_f32_e32 v76, v76
	s_nop 0
	v_mul_f32_e32 v77, 0x45800000, v76
	v_cndmask_b32_e32 v76, v76, v77, vcc
	v_pk_mul_f32 v[78:79], v[78:79], v[76:77] op_sel_hi:[1,0]
	v_pk_mul_f32 v[80:81], v[82:83], v[76:77] op_sel_hi:[1,0]
	v_cvt_pk_f16_f32 v78, v78, v79
	v_cvt_pk_f16_f32 v79, v80, v81
	global_store_dwordx2 v[72:73], v[78:79], off
	v_pk_mul_f32 v[78:79], v[86:87], v[76:77] op_sel_hi:[1,0]
	v_pk_mul_f32 v[80:81], v[90:91], v[76:77] op_sel_hi:[1,0]
	v_cvt_pk_f16_f32 v78, v78, v79
	v_cvt_pk_f16_f32 v79, v80, v81
	global_store_dwordx2 v[72:73], v[78:79], off offset:1024
	v_pk_mul_f32 v[78:79], v[94:95], v[76:77] op_sel_hi:[1,0]
	v_pk_mul_f32 v[64:65], v[64:65], v[76:77] op_sel_hi:[1,0]
	v_cvt_pk_f16_f32 v78, v78, v79
	v_cvt_pk_f16_f32 v79, v64, v65
	v_fma_mixlo_f16 v77, v68, v76, 0
	v_pk_mov_b32 v[64:65], v[68:69], v[74:75] op_sel:[1,0]
	v_fma_mixlo_f16 v68, v75, v76, 0
	v_pk_mul_f32 v[64:65], v[64:65], v[76:77] op_sel_hi:[1,0]
	global_store_dwordx2 v[72:73], v[78:79], off offset:2048
	v_cvt_pk_f16_f32 v65, v64, v65
	v_pack_b32_f16 v64, v77, v65
	v_alignbit_b32 v65, v68, v65, 16
	global_store_dwordx2 v[72:73], v[64:65], off offset:3072

.LBB0_902:
	s_andn2_saveexec_b64 s[14:15], s[14:15]
	s_cbranch_execz .LBB0_904
	s_waitcnt vmcnt(13)
	v_mov_b32_e32 v72, v45
	v_mov_b32_e32 v73, v46
	v_mov_b32_e32 v74, v44
	v_mov_b32_e32 v75, v47
	v_pk_add_f32 v[72:73], v[72:73], v[74:75]
	v_mov_b32_e32 v74, v41
	v_mov_b32_e32 v75, v42
	s_waitcnt vmcnt(12)
	v_mov_b32_e32 v76, v40
	v_mov_b32_e32 v77, v43
	v_pk_add_f32 v[74:75], v[74:75], v[76:77]
	v_add_f32_e32 v65, v72, v73
	v_pk_add_f32 v[74:75], v[74:75], v[74:75] op_sel:[0,1] op_sel_hi:[1,0]
	v_add_f32_e32 v72, 0, v65
	v_add_f32_e32 v76, v36, v37
	v_add_f32_e32 v78, v38, v39
	v_mov_b32_e32 v73, v32
	v_mov_b32_e32 v75, v33
	v_mov_b32_e32 v77, v34
	v_mov_b32_e32 v79, v35
	v_pk_add_f32 v[72:73], v[72:73], v[74:75]
	v_pk_add_f32 v[74:75], v[76:77], v[78:79]
	v_cmp_lt_i32_e32 vcc, v203, v201
	v_pk_add_f32 v[72:73], v[72:73], v[74:75]
	s_mov_b32 s17, 0x800000
	v_cndmask_b32_e32 v67, v199, v203, vcc
	v_add_f32_e32 v65, v72, v73
	v_lshlrev_b32_e32 v67, 2, v67
	ds_bpermute_b32 v72, v67, v65
	v_cmp_lt_i32_e32 vcc, v202, v201
	s_waitcnt lgkmcnt(0)
	v_add_f32_e32 v65, v65, v72
	v_cndmask_b32_e32 v72, v199, v202, vcc
	s_waitcnt vmcnt(5)
	v_lshlrev_b32_e32 v104, 2, v72
	ds_bpermute_b32 v72, v104, v65
	s_waitcnt lgkmcnt(0)
	v_add_f32_e32 v65, v65, v72
	v_mul_f32_e32 v72, 0x3c800000, v65
	v_pk_add_f32 v[82:83], v[44:45], v[72:73] op_sel_hi:[1,0] neg_lo:[0,1] neg_hi:[0,1]
	v_pk_add_f32 v[86:87], v[46:47], v[72:73] op_sel_hi:[1,0] neg_lo:[0,1] neg_hi:[0,1]
	v_pk_mul_f32 v[84:85], v[82:83], v[82:83]
	v_pk_mul_f32 v[88:89], v[86:87], v[86:87]
	v_add_f32_e32 v65, v84, v85
	v_pk_add_f32 v[90:91], v[40:41], v[72:73] op_sel_hi:[1,0] neg_lo:[0,1] neg_hi:[0,1]
	v_add_f32_e32 v65, v88, v65
	v_pk_mul_f32 v[92:93], v[90:91], v[90:91]
	v_add_f32_e32 v65, v89, v65
	v_pk_add_f32 v[94:95], v[42:43], v[72:73] op_sel_hi:[1,0] neg_lo:[0,1] neg_hi:[0,1]
	v_add_f32_e32 v65, v92, v65
	v_pk_mul_f32 v[96:97], v[94:95], v[94:95]
	v_add_f32_e32 v65, v93, v65
	v_pk_add_f32 v[98:99], v[36:37], v[72:73] op_sel_hi:[1,0] neg_lo:[0,1] neg_hi:[0,1]
	v_add_f32_e32 v65, v96, v65
	v_pk_mul_f32 v[100:101], v[98:99], v[98:99]
	v_add_f32_e32 v65, v97, v65
	v_pk_add_f32 v[74:75], v[32:33], v[72:73] op_sel_hi:[1,0] neg_lo:[0,1] neg_hi:[0,1]
	v_pk_add_f32 v[78:79], v[34:35], v[72:73] op_sel_hi:[1,0] neg_lo:[0,1] neg_hi:[0,1]
	v_pk_add_f32 v[72:73], v[38:39], v[72:73] op_sel_hi:[1,0] neg_lo:[0,1] neg_hi:[0,1]
	v_add_f32_e32 v65, v100, v65
	v_pk_mul_f32 v[102:103], v[72:73], v[72:73]
	v_add_f32_e32 v65, v101, v65
	v_add_f32_e32 v65, v102, v65
	v_pk_mul_f32 v[76:77], v[74:75], v[74:75]
	v_add_f32_e32 v65, v103, v65
	v_add_f32_e32 v65, v76, v65
	v_pk_mul_f32 v[80:81], v[78:79], v[78:79]
	v_add_f32_e32 v65, v77, v65
	v_add_f32_e32 v65, v80, v65
	v_add_f32_e32 v65, v81, v65
	ds_bpermute_b32 v67, v67, v65
	v_lshlrev_b32_e32 v80, 1, v71
	v_mov_b32_e32 v81, v177
	s_waitcnt lgkmcnt(0)
	v_add_f32_e32 v65, v65, v67
	ds_bpermute_b32 v67, v104, v65
	v_add_u32_e32 v76, 0x1ff0, v68
	v_lshrrev_b32_e32 v76, 14, v76
	v_mul_u32_u24_e32 v77, 0x2010, v76
	v_sub_u32_e32 v77, v68, v77
	v_min_u32_e32 v77, 0x205f, v77
	v_mul_u32_u24_e32 v76, 0x101000, v76
	v_lshl_add_u32 v76, v77, 7, v76
	v_and_b32_e32 v77, 31, v77
	v_mul_u32_u24_e32 v77, 0x70, v77
	v_sub_u32_e32 v76, v76, v77
	v_and_b32_e32 v77, 16, v80
	v_lshl_add_u32 v76, v77, 5, v76
	v_and_b32_e32 v77, 8, v80
	v_add_u32_e32 v76, v76, v77
	v_mov_b32_e32 v77, 0
	v_lshl_add_u64 v[76:77], s[8:9], 0, v[76:77]
	s_waitcnt lgkmcnt(0)
	v_add_f32_e32 v65, v65, v67
	v_fmamk_f32 v65, v65, 0x3c800000, v196
	v_mul_f32_e32 v67, 0x4b800000, v65
	v_cmp_gt_f32_e32 vcc, s17, v65
	s_nop 1
	v_cndmask_b32_e32 v65, v65, v67, vcc
	v_rsq_f32_e32 v65, v65
	s_nop 0
	v_mul_f32_e32 v67, 0x45800000, v65
	v_cndmask_b32_e32 v80, v65, v67, vcc
	v_pk_mul_f32 v[82:83], v[82:83], v[80:81] op_sel_hi:[1,0]
	v_pk_mul_f32 v[84:85], v[86:87], v[80:81] op_sel_hi:[1,0]
	v_cvt_pk_f16_f32 v82, v82, v83
	v_cvt_pk_f16_f32 v83, v84, v85
	global_store_dwordx2 v[76:77], v[82:83], off
	v_pk_mul_f32 v[82:83], v[90:91], v[80:81] op_sel_hi:[1,0]
	v_pk_mul_f32 v[84:85], v[94:95], v[80:81] op_sel_hi:[1,0]
	v_cvt_pk_f16_f32 v82, v82, v83
	v_cvt_pk_f16_f32 v83, v84, v85
	global_store_dwordx2 v[76:77], v[82:83], off offset:1024
	v_pk_mul_f32 v[82:83], v[98:99], v[80:81] op_sel_hi:[1,0]
	v_pk_mul_f32 v[72:73], v[72:73], v[80:81] op_sel_hi:[1,0]
	v_cvt_pk_f16_f32 v82, v82, v83
	v_cvt_pk_f16_f32 v83, v72, v73
	v_pk_mov_b32 v[72:73], v[74:75], v[78:79] op_sel:[1,0]
	v_fma_mixlo_f16 v65, v74, v80, 0
	v_pk_mul_f32 v[72:73], v[72:73], v[80:81] op_sel_hi:[1,0]
	global_store_dwordx2 v[76:77], v[82:83], off offset:2048
	v_cvt_pk_f16_f32 v67, v72, v73
	v_pack_b32_f16 v72, v65, v67
	v_fma_mixlo_f16 v65, v79, v80, 0
	v_alignbit_b32 v73, v65, v67, 16
	global_store_dwordx2 v[76:77], v[72:73], off offset:3072

.LBB0_914:
	s_andn2_saveexec_b64 s[14:15], s[14:15]
	s_cbranch_execz .LBB0_916
	s_waitcnt vmcnt(13)
	v_mov_b32_e32 v72, v29
	v_mov_b32_e32 v73, v30
	v_mov_b32_e32 v74, v28
	v_mov_b32_e32 v75, v31
	v_pk_add_f32 v[72:73], v[72:73], v[74:75]
	v_mov_b32_e32 v74, v25
	v_mov_b32_e32 v75, v26
	s_waitcnt vmcnt(12)
	v_mov_b32_e32 v76, v24
	v_mov_b32_e32 v77, v27
	v_pk_add_f32 v[74:75], v[74:75], v[76:77]
	v_add_f32_e32 v65, v72, v73
	v_pk_add_f32 v[74:75], v[74:75], v[74:75] op_sel:[0,1] op_sel_hi:[1,0]
	v_add_f32_e32 v72, 0, v65
	v_add_f32_e32 v76, v20, v21
	v_add_f32_e32 v78, v22, v23
	v_mov_b32_e32 v73, v16
	v_mov_b32_e32 v75, v17
	v_mov_b32_e32 v77, v18
	v_mov_b32_e32 v79, v19
	v_pk_add_f32 v[72:73], v[72:73], v[74:75]
	v_pk_add_f32 v[74:75], v[76:77], v[78:79]
	v_cmp_lt_i32_e32 vcc, v203, v201
	v_pk_add_f32 v[72:73], v[72:73], v[74:75]
	s_mov_b32 s17, 0x800000
	v_cndmask_b32_e32 v67, v199, v203, vcc
	v_add_f32_e32 v65, v72, v73
	v_lshlrev_b32_e32 v67, 2, v67
	ds_bpermute_b32 v72, v67, v65
	v_cmp_lt_i32_e32 vcc, v202, v201
	s_waitcnt lgkmcnt(0)
	v_add_f32_e32 v65, v65, v72
	v_cndmask_b32_e32 v72, v199, v202, vcc
	s_waitcnt vmcnt(5)
	v_lshlrev_b32_e32 v104, 2, v72
	ds_bpermute_b32 v72, v104, v65
	s_waitcnt lgkmcnt(0)
	v_add_f32_e32 v65, v65, v72
	v_mul_f32_e32 v72, 0x3c800000, v65
	v_pk_add_f32 v[82:83], v[28:29], v[72:73] op_sel_hi:[1,0] neg_lo:[0,1] neg_hi:[0,1]
	v_pk_add_f32 v[86:87], v[30:31], v[72:73] op_sel_hi:[1,0] neg_lo:[0,1] neg_hi:[0,1]
	v_pk_mul_f32 v[84:85], v[82:83], v[82:83]
	v_pk_mul_f32 v[88:89], v[86:87], v[86:87]
	v_add_f32_e32 v65, v84, v85
	v_pk_add_f32 v[90:91], v[24:25], v[72:73] op_sel_hi:[1,0] neg_lo:[0,1] neg_hi:[0,1]
	v_add_f32_e32 v65, v88, v65
	v_pk_mul_f32 v[92:93], v[90:91], v[90:91]
	v_add_f32_e32 v65, v89, v65
	v_pk_add_f32 v[94:95], v[26:27], v[72:73] op_sel_hi:[1,0] neg_lo:[0,1] neg_hi:[0,1]
	v_add_f32_e32 v65, v92, v65
	v_pk_mul_f32 v[96:97], v[94:95], v[94:95]
	v_add_f32_e32 v65, v93, v65
	v_pk_add_f32 v[98:99], v[20:21], v[72:73] op_sel_hi:[1,0] neg_lo:[0,1] neg_hi:[0,1]
	v_add_f32_e32 v65, v96, v65
	v_pk_mul_f32 v[100:101], v[98:99], v[98:99]
	v_add_f32_e32 v65, v97, v65
	v_pk_add_f32 v[74:75], v[16:17], v[72:73] op_sel_hi:[1,0] neg_lo:[0,1] neg_hi:[0,1]
	v_pk_add_f32 v[78:79], v[18:19], v[72:73] op_sel_hi:[1,0] neg_lo:[0,1] neg_hi:[0,1]
	v_pk_add_f32 v[72:73], v[22:23], v[72:73] op_sel_hi:[1,0] neg_lo:[0,1] neg_hi:[0,1]
	v_add_f32_e32 v65, v100, v65
	v_pk_mul_f32 v[102:103], v[72:73], v[72:73]
	v_add_f32_e32 v65, v101, v65
	v_add_f32_e32 v65, v102, v65
	v_pk_mul_f32 v[76:77], v[74:75], v[74:75]
	v_add_f32_e32 v65, v103, v65
	v_add_f32_e32 v65, v76, v65
	v_pk_mul_f32 v[80:81], v[78:79], v[78:79]
	v_add_f32_e32 v65, v77, v65
	v_add_f32_e32 v65, v80, v65
	v_add_f32_e32 v65, v81, v65
	ds_bpermute_b32 v67, v67, v65
	v_lshlrev_b32_e32 v80, 1, v71
	v_mov_b32_e32 v81, v177
	s_waitcnt lgkmcnt(0)
	v_add_f32_e32 v65, v65, v67
	ds_bpermute_b32 v67, v104, v65
	v_add_u32_e32 v76, 0x1ff0, v68
	v_lshrrev_b32_e32 v76, 14, v76
	v_mul_u32_u24_e32 v77, 0x2010, v76
	v_sub_u32_e32 v77, v68, v77
	v_min_u32_e32 v77, 0x205f, v77
	v_mul_u32_u24_e32 v76, 0x101000, v76
	v_lshl_add_u32 v76, v77, 7, v76
	v_and_b32_e32 v77, 31, v77
	v_mul_u32_u24_e32 v77, 0x70, v77
	v_sub_u32_e32 v76, v76, v77
	v_and_b32_e32 v77, 16, v80
	v_lshl_add_u32 v76, v77, 5, v76
	v_and_b32_e32 v77, 8, v80
	v_add_u32_e32 v76, v76, v77
	v_mov_b32_e32 v77, 0
	v_lshl_add_u64 v[76:77], s[8:9], 0, v[76:77]
	s_waitcnt lgkmcnt(0)
	v_add_f32_e32 v65, v65, v67
	v_fmamk_f32 v65, v65, 0x3c800000, v196
	v_mul_f32_e32 v67, 0x4b800000, v65
	v_cmp_gt_f32_e32 vcc, s17, v65
	s_nop 1
	v_cndmask_b32_e32 v65, v65, v67, vcc
	v_rsq_f32_e32 v65, v65
	s_nop 0
	v_mul_f32_e32 v67, 0x45800000, v65
	v_cndmask_b32_e32 v80, v65, v67, vcc
	v_pk_mul_f32 v[82:83], v[82:83], v[80:81] op_sel_hi:[1,0]
	v_pk_mul_f32 v[84:85], v[86:87], v[80:81] op_sel_hi:[1,0]
	v_cvt_pk_f16_f32 v82, v82, v83
	v_cvt_pk_f16_f32 v83, v84, v85
	global_store_dwordx2 v[76:77], v[82:83], off
	v_pk_mul_f32 v[82:83], v[90:91], v[80:81] op_sel_hi:[1,0]
	v_pk_mul_f32 v[84:85], v[94:95], v[80:81] op_sel_hi:[1,0]
	v_cvt_pk_f16_f32 v82, v82, v83
	v_cvt_pk_f16_f32 v83, v84, v85
	global_store_dwordx2 v[76:77], v[82:83], off offset:1024
	v_pk_mul_f32 v[82:83], v[98:99], v[80:81] op_sel_hi:[1,0]
	v_pk_mul_f32 v[72:73], v[72:73], v[80:81] op_sel_hi:[1,0]
	v_cvt_pk_f16_f32 v82, v82, v83
	v_cvt_pk_f16_f32 v83, v72, v73
	v_pk_mov_b32 v[72:73], v[74:75], v[78:79] op_sel:[1,0]
	v_fma_mixlo_f16 v65, v74, v80, 0
	v_pk_mul_f32 v[72:73], v[72:73], v[80:81] op_sel_hi:[1,0]
	global_store_dwordx2 v[76:77], v[82:83], off offset:2048
	v_cvt_pk_f16_f32 v67, v72, v73
	v_pack_b32_f16 v72, v65, v67
	v_fma_mixlo_f16 v65, v79, v80, 0
	v_alignbit_b32 v73, v65, v67, 16
	global_store_dwordx2 v[76:77], v[72:73], off offset:3072

.LBB0_926:
	s_andn2_saveexec_b64 s[0:1], s[0:1]
	s_cbranch_execz .LBB0_928
	v_mov_b32_e32 v68, v13
	v_mov_b32_e32 v69, v14
	s_waitcnt vmcnt(13)
	v_mov_b32_e32 v72, v12
	v_mov_b32_e32 v73, v15
	v_pk_add_f32 v[68:69], v[68:69], v[72:73]
	v_mov_b32_e32 v72, v9
	v_mov_b32_e32 v73, v10
	v_mov_b32_e32 v74, v8
	v_mov_b32_e32 v75, v11
	v_pk_add_f32 v[72:73], v[72:73], v[74:75]
	v_add_f32_e32 v65, v68, v69
	v_pk_add_f32 v[72:73], v[72:73], v[72:73] op_sel:[0,1] op_sel_hi:[1,0]
	v_add_f32_e32 v68, 0, v65
	v_add_f32_e32 v74, v4, v5
	s_waitcnt vmcnt(12)
	v_add_f32_e32 v76, v6, v7
	v_mov_b32_e32 v69, v0
	v_mov_b32_e32 v73, v1
	v_mov_b32_e32 v75, v2
	v_mov_b32_e32 v77, v3
	v_pk_add_f32 v[68:69], v[68:69], v[72:73]
	v_pk_add_f32 v[72:73], v[74:75], v[76:77]
	v_cmp_lt_i32_e32 vcc, v203, v201
	v_pk_add_f32 v[68:69], v[68:69], v[72:73]
	s_mov_b32 s4, 0x800000
	v_add_f32_e32 v65, v68, v69
	v_cndmask_b32_e32 v68, v199, v203, vcc
	s_waitcnt vmcnt(6)
	v_lshlrev_b32_e32 v102, 2, v68
	ds_bpermute_b32 v68, v102, v65
	v_cmp_lt_i32_e32 vcc, v202, v201
	s_waitcnt lgkmcnt(0)
	v_add_f32_e32 v65, v65, v68
	v_cndmask_b32_e32 v68, v199, v202, vcc
	v_lshlrev_b32_e32 v103, 2, v68
	ds_bpermute_b32 v68, v103, v65
	s_waitcnt lgkmcnt(0)
	v_add_f32_e32 v65, v65, v68
	v_mul_f32_e32 v68, 0x3c800000, v65
	v_pk_add_f32 v[80:81], v[12:13], v[68:69] op_sel_hi:[1,0] neg_lo:[0,1] neg_hi:[0,1]
	v_pk_add_f32 v[84:85], v[14:15], v[68:69] op_sel_hi:[1,0] neg_lo:[0,1] neg_hi:[0,1]
	v_pk_mul_f32 v[82:83], v[80:81], v[80:81]
	v_pk_mul_f32 v[86:87], v[84:85], v[84:85]
	v_add_f32_e32 v65, v82, v83
	v_pk_add_f32 v[88:89], v[8:9], v[68:69] op_sel_hi:[1,0] neg_lo:[0,1] neg_hi:[0,1]
	v_add_f32_e32 v65, v86, v65
	v_pk_mul_f32 v[90:91], v[88:89], v[88:89]
	v_add_f32_e32 v65, v87, v65
	v_pk_add_f32 v[92:93], v[10:11], v[68:69] op_sel_hi:[1,0] neg_lo:[0,1] neg_hi:[0,1]
	v_add_f32_e32 v65, v90, v65
	v_pk_mul_f32 v[94:95], v[92:93], v[92:93]
	v_add_f32_e32 v65, v91, v65
	v_pk_add_f32 v[96:97], v[4:5], v[68:69] op_sel_hi:[1,0] neg_lo:[0,1] neg_hi:[0,1]
	v_add_f32_e32 v65, v94, v65
	v_pk_mul_f32 v[98:99], v[96:97], v[96:97]
	v_add_f32_e32 v65, v95, v65
	v_pk_add_f32 v[72:73], v[0:1], v[68:69] op_sel_hi:[1,0] neg_lo:[0,1] neg_hi:[0,1]
	v_pk_add_f32 v[76:77], v[2:3], v[68:69] op_sel_hi:[1,0] neg_lo:[0,1] neg_hi:[0,1]
	v_pk_add_f32 v[68:69], v[6:7], v[68:69] op_sel_hi:[1,0] neg_lo:[0,1] neg_hi:[0,1]
	v_add_f32_e32 v65, v98, v65
	v_pk_mul_f32 v[100:101], v[68:69], v[68:69]
	v_add_f32_e32 v65, v99, v65
	v_add_f32_e32 v65, v100, v65
	v_pk_mul_f32 v[74:75], v[72:73], v[72:73]
	v_add_f32_e32 v65, v101, v65
	v_add_f32_e32 v65, v74, v65
	v_pk_mul_f32 v[78:79], v[76:77], v[76:77]
	v_add_f32_e32 v65, v75, v65
	v_add_f32_e32 v65, v78, v65
	v_add_f32_e32 v65, v79, v65
	ds_bpermute_b32 v74, v102, v65
	v_mov_b32_e32 v79, v177
	s_waitcnt lgkmcnt(0)
	v_add_f32_e32 v65, v65, v74
	ds_bpermute_b32 v78, v103, v65
	s_waitcnt lgkmcnt(0)
	v_add_f32_e32 v65, v65, v78
	v_fmamk_f32 v65, v65, 0x3c800000, v196
	v_mul_f32_e32 v78, 0x4b800000, v65
	v_cmp_gt_f32_e32 vcc, s4, v65
	s_nop 1
	v_cndmask_b32_e32 v65, v65, v78, vcc
	v_rsq_f32_e32 v65, v65
	v_lshlrev_b32_e32 v78, 1, v71
	v_add_u32_e32 v74, 0x1ff0, v66
	v_lshrrev_b32_e32 v74, 14, v74
	v_mul_u32_u24_e32 v75, 0x2010, v74
	v_sub_u32_e32 v75, v66, v75
	v_min_u32_e32 v75, 0x205f, v75
	v_mul_u32_u24_e32 v74, 0x101000, v74
	v_lshl_add_u32 v74, v75, 7, v74
	v_and_b32_e32 v75, 31, v75
	v_mul_u32_u24_e32 v75, 0x70, v75
	v_sub_u32_e32 v74, v74, v75
	v_and_b32_e32 v75, 16, v78
	v_lshl_add_u32 v74, v75, 5, v74
	v_and_b32_e32 v75, 8, v78
	v_add_u32_e32 v74, v74, v75
	v_mov_b32_e32 v75, 0
	v_lshl_add_u64 v[74:75], s[8:9], 0, v[74:75]
	v_mul_f32_e32 v71, 0x45800000, v65
	v_cndmask_b32_e32 v78, v65, v71, vcc
	v_pk_mul_f32 v[80:81], v[80:81], v[78:79] op_sel_hi:[1,0]
	v_pk_mul_f32 v[82:83], v[84:85], v[78:79] op_sel_hi:[1,0]
	v_cvt_pk_f16_f32 v80, v80, v81
	v_cvt_pk_f16_f32 v81, v82, v83
	global_store_dwordx2 v[74:75], v[80:81], off
	v_pk_mul_f32 v[80:81], v[88:89], v[78:79] op_sel_hi:[1,0]
	v_pk_mul_f32 v[82:83], v[92:93], v[78:79] op_sel_hi:[1,0]
	v_cvt_pk_f16_f32 v80, v80, v81
	v_cvt_pk_f16_f32 v81, v82, v83
	global_store_dwordx2 v[74:75], v[80:81], off offset:1024
	v_pk_mul_f32 v[80:81], v[96:97], v[78:79] op_sel_hi:[1,0]
	v_pk_mul_f32 v[68:69], v[68:69], v[78:79] op_sel_hi:[1,0]
	v_cvt_pk_f16_f32 v80, v80, v81
	v_cvt_pk_f16_f32 v81, v68, v69
	v_pk_mov_b32 v[68:69], v[72:73], v[76:77] op_sel:[1,0]
	v_fma_mixlo_f16 v65, v72, v78, 0
	v_pk_mul_f32 v[68:69], v[68:69], v[78:79] op_sel_hi:[1,0]
	global_store_dwordx2 v[74:75], v[80:81], off offset:2048
	v_cvt_pk_f16_f32 v69, v68, v69
	v_pack_b32_f16 v68, v65, v69
	v_fma_mixlo_f16 v65, v77, v78, 0
	v_alignbit_b32 v69, v65, v69, 16
	global_store_dwordx2 v[74:75], v[68:69], off offset:3072
